# memory-attention key RMS butterfly via DPP lane moves instead of ds_bpermute; k-mean sums batched
# speedup vs baseline: 1.0062x; 1.0049x over previous
; #define LAS __attribute__((address_space(3)))
; __device__ __forceinline__ float bflo(unsigned u) { return __uint_as_float(u << 16); }
; __device__ __forceinline__ float bfhi(unsigned u) { return __uint_as_float(u & 0xffff0000u); }
; __device__ __forceinline__ float frsq(float x) { return __builtin_amdgcn_rsqf(x); }
; __device__ __forceinline__ int otid() { int t = threadIdx.x; asm volatile("" : "+v"(t)); return t; }
; #define MEM_LOAD(kt) do { _Pragma("unroll") for (int ii = 0; ii < 2; ++ii) { const int cid = tid + 512 * ii; \
;         ukr[ii] = *(const u32x4*)(kvm + (size_t)((kt) * 64 + (cid >> 4)) * 1024 + hm * 128 + (cid & 15) * 8); \
;         uvr[ii] = *(const u32x4*)(kvm + (size_t)((kt) * 64 + (cid >> 4)) * 1024 + 512 + hm * 128 + (cid & 15) * 8); } } while (0)
; __device__ __forceinline__ void mem_unit(const Args& a, int l, LAS unsigned char* lds, int b, int hm, int qb) {
;     const int tid = otid(), lane = tid & 63, w = __builtin_amdgcn_readfirstlane(tid >> 6), fr = lane & 15, fq = lane >> 4;
;     bf16_t* proj = (bf16_t*)(a.ws + WS_PROJ);
;     const bf16_t* kvm = (const bf16_t*)(a.ws + WS_KVM) + (size_t)b * MEML * 1024;
;     const size_t rowbase = (size_t)b * SEQ; const int q0 = qb * 256 + w * 32;
;     u32x4 ukr[2], uvr[2];
;     ...
;     const f32x4 g0 = *(const f32x4*)(a.memkn + l * 128 + (tid & 15) * 8), g1 = *(const f32x4*)(a.memkn + l * 128 + (tid & 15) * 8 + 4);
;     MEM_LOAD(0);
;     bf16x8 qf[2][4];
; #pragma unroll
;     for (int qt = 0; qt < 2; ++qt) {
;         u32x4 u[4]; float ss = 0.f;
; #pragma unroll
;         for (int ks = 0; ks < 4; ++ks) { u[ks] = *(const u32x4*)(proj + (rowbase + q0 + qt * 16 + fr) * NCOL + CQM + hm * 128 + ks * 32 + fq * 8);
;             ss += bflo(u[ks].x) * bflo(u[ks].x) + bfhi(u[ks].x) * bfhi(u[ks].x) + bflo(u[ks].y) * bflo(u[ks].y) + bfhi(u[ks].y) * bfhi(u[ks].y)
;                 + bflo(u[ks].z) * bflo(u[ks].z) + bfhi(u[ks].z) * bfhi(u[ks].z) + bflo(u[ks].w) * bflo(u[ks].w) + bfhi(u[ks].w) * bfhi(u[ks].w); }
;         ss += __shfl_xor(ss, 16); ss += __shfl_xor(ss, 32);
;         const float r = frsq(ss * (1.f / 128.f) + EPS) * (0.08838834764831845f * LOG2E);
; __global__ void __launch_bounds__(512) hymba_fwd(Args a) {
;     ...
;             for (int u0 = bx; u0 < 256; u0 += G) { const int u = (G == 256) ? (u0 & 7) * 32 + (u0 >> 3) : u0;
;                 mem_unit(a, l, lds, u >> 5, (u >> 3) & 3, u & 7); }
.LBB0_519:
	s_lshl_b32 s4, s14, 5
	s_and_b32 s4, s4, 0xe0
	s_ashr_i32 s5, s14, 3
	s_add_i32 s6, s4, s5
	s_and_b64 s[4:5], s[54:55], exec
	s_cselect_b32 s4, s6, s14
	s_ashr_i32 s8, s4, 5
	s_ashr_i32 s9, s8, 31
	v_mov_b32_e32 v96, v178
	s_lshl_b64 s[40:41], s[8:9], 19
	s_add_u32 s10, s90, s40
	v_ashrrev_i32_e32 v94, 4, v96
	s_addc_u32 s11, s91, s41
	s_lshl_b32 s6, s4, 4
	v_ashrrev_i32_e32 v95, 31, v94
	s_lshl_b64 s[16:17], s[8:9], 11
	v_lshlrev_b32_e32 v0, 3, v96
	s_and_b32 s8, s6, 0x180
	v_lshlrev_b64 v[88:89], 11, v[94:95]
	v_and_b32_e32 v10, 0x78, v0
	v_lshl_add_u64 v[8:9], s[10:11], 0, v[88:89]
	s_lshl_b32 s6, s8, 1
	v_lshl_add_u64 v[8:9], v[8:9], 0, s[6:7]
	v_lshlrev_b32_e32 v144, 1, v10
	v_lshlrev_b32_e32 v4, 2, v10
	v_lshl_add_u64 v[8:9], v[8:9], 0, v[144:145]
	v_readfirstlane_b32 s5, v96
	global_load_dwordx4 v[0:3], v4, s[42:43] offset:16
	s_nop 0
	global_load_dwordx4 v[4:7], v4, s[42:43]
	s_nop 0
	global_load_dwordx4 v[52:55], v[8:9], off
	global_load_dwordx4 v[48:51], v[8:9], off offset:1024
	v_add_u32_e32 v8, 0x200, v96
	s_ashr_i32 s5, s5, 1
	v_ashrrev_i32_e32 v92, 4, v8
	s_lshl_b32 s9, s4, 8
	s_andn2_b32 s5, s5, 31
	v_ashrrev_i32_e32 v93, 31, v92
	s_and_b32 s9, s9, 0x700
	v_lshlrev_b64 v[90:91], 11, v[92:93]
	s_add_i32 s5, s5, s9
	v_lshl_add_u64 v[8:9], s[10:11], 0, v[90:91]
	s_ashr_i32 s9, s5, 31
	v_lshl_add_u64 v[8:9], v[8:9], 0, s[6:7]
	s_add_u32 s5, s16, s5
	v_lshl_add_u64 v[8:9], v[8:9], 0, v[144:145]
	v_and_b32_e32 v93, 15, v96
	s_addc_u32 s9, s17, s9
	global_load_dwordx4 v[44:47], v[8:9], off
	global_load_dwordx4 v[40:43], v[8:9], off offset:1024
	v_or_b32_e32 v8, s5, v93
	v_mov_b32_e32 v9, s9
	v_lshlrev_b64 v[72:73], 13, v[8:9]
	v_bfe_u32 v95, v96, 4, 2
	v_lshl_add_u64 v[162:163], s[84:85], 0, v[72:73]
	v_lshl_add_u64 v[160:161], v[162:163], 0, s[6:7]
	v_lshlrev_b32_e32 v144, 4, v95
	v_lshl_add_u64 v[12:13], v[160:161], 0, v[144:145]
	v_lshlrev_b32_e32 v16, 5, v95
	global_load_dwordx4 v[8:11], v[12:13], off offset:2048
	global_load_dwordx4 v[18:21], v[12:13], off offset:2112
	global_load_dwordx4 v[98:101], v[12:13], off offset:2176
	s_nop 0
	global_load_dwordx4 v[12:15], v[12:13], off offset:2240
	s_nop 0
	global_load_dwordx4 v[68:71], v16, s[44:45] offset:16
	global_load_dwordx4 v[24:27], v16, s[44:45]
	global_load_dwordx4 v[64:67], v16, s[44:45] offset:144
	global_load_dwordx4 v[28:31], v16, s[44:45] offset:128
	global_load_dwordx4 v[60:63], v16, s[44:45] offset:272
	global_load_dwordx4 v[36:39], v16, s[44:45] offset:256
	global_load_dwordx4 v[56:59], v16, s[44:45] offset:400
	global_load_dwordx4 v[32:35], v16, s[44:45] offset:384
	v_or_b32_e32 v72, 0x20000, v72
	v_lshl_add_u64 v[158:159], s[84:85], 0, v[72:73]
	v_lshl_add_u64 v[156:157], v[158:159], 0, s[6:7]
	v_readlane_b32 s5, v244, 52
	v_mul_lo_u32 v174, v94, s31
	v_mul_lo_u32 v175, v94, s27
	v_mul_lo_u32 v177, v92, s31
	v_mul_lo_u32 v180, v92, s27
	s_lshl_b32 s4, s4, 5
	s_and_b32 s4, s4, 0x300
	s_mov_b32 s6, 0
	s_mov_b64 s[46:47], 0
	s_waitcnt vmcnt(9)
	v_lshlrev_b32_e32 v84, 16, v99
	s_waitcnt vmcnt(8)
	v_lshlrev_b32_e32 v78, 16, v13
	v_and_b32_e32 v79, 0xffff0000, v13
	v_and_b32_e32 v81, 0xffff0000, v12
	v_and_b32_e32 v13, 0xffff0000, v98
	v_lshlrev_b32_e32 v80, 16, v12
	v_lshlrev_b32_e32 v12, 16, v98
	v_mov_b32_e32 v106, v13
	v_mov_b32_e32 v107, v81
	v_mov_b32_e32 v104, v12
	v_mov_b32_e32 v105, v80
	v_pk_mul_f32 v[106:107], v[106:107], v[106:107]
	v_lshlrev_b32_e32 v74, 16, v15
	v_and_b32_e32 v75, 0xffff0000, v15
	v_lshlrev_b32_e32 v76, 16, v14
	v_and_b32_e32 v77, 0xffff0000, v14
	v_lshlrev_b32_e32 v82, 16, v101
	v_and_b32_e32 v83, 0xffff0000, v101
	v_lshlrev_b32_e32 v14, 16, v100
	v_and_b32_e32 v15, 0xffff0000, v100
	v_and_b32_e32 v85, 0xffff0000, v99
	v_mov_b32_e32 v100, v84
	v_mov_b32_e32 v101, v78
	v_pk_fma_f32 v[104:105], v[104:105], v[104:105], v[106:107]
	v_mov_b32_e32 v102, v85
	v_mov_b32_e32 v103, v79
	v_pk_fma_f32 v[100:101], v[100:101], v[100:101], v[104:105]
	v_mov_b32_e32 v86, v14
	v_mov_b32_e32 v87, v76
	v_pk_fma_f32 v[100:101], v[102:103], v[102:103], v[100:101]
	v_mov_b32_e32 v98, v15
	v_mov_b32_e32 v99, v77
	v_pk_fma_f32 v[86:87], v[86:87], v[86:87], v[100:101]
	v_mov_b32_e32 v16, v82
	v_mov_b32_e32 v17, v74
	v_pk_fma_f32 v[86:87], v[98:99], v[98:99], v[86:87]
	v_mov_b32_e32 v22, v83
	v_mov_b32_e32 v23, v75
	v_pk_fma_f32 v[16:17], v[16:17], v[16:17], v[86:87]
	v_lshlrev_b32_e32 v86, 16, v21
	v_and_b32_e32 v87, 0xffff0000, v21
	v_and_b32_e32 v21, 0xffff0000, v18
	v_and_b32_e32 v103, 0xffff0000, v8
	v_pk_fma_f32 v[16:17], v[22:23], v[22:23], v[16:17]
	v_lshlrev_b32_e32 v22, 16, v20
	v_and_b32_e32 v23, 0xffff0000, v20
	v_lshlrev_b32_e32 v20, 16, v18
	v_lshlrev_b32_e32 v102, 16, v8
	v_mov_b32_e32 v116, v103
	v_mov_b32_e32 v117, v21
	v_lshlrev_b32_e32 v98, 16, v19
	v_and_b32_e32 v99, 0xffff0000, v19
	v_lshlrev_b32_e32 v18, 16, v10
	v_and_b32_e32 v19, 0xffff0000, v10
	v_lshlrev_b32_e32 v10, 16, v9
	v_mov_b32_e32 v114, v102
	v_mov_b32_e32 v115, v20
	v_pk_mul_f32 v[116:117], v[116:117], v[116:117]
	v_lshlrev_b32_e32 v100, 16, v11
	v_and_b32_e32 v101, 0xffff0000, v11
	v_and_b32_e32 v11, 0xffff0000, v9
	v_mov_b32_e32 v110, v10
	v_mov_b32_e32 v111, v98
	v_pk_fma_f32 v[114:115], v[114:115], v[114:115], v[116:117]
	v_mov_b32_e32 v112, v11
	v_mov_b32_e32 v113, v99
	v_pk_fma_f32 v[110:111], v[110:111], v[110:111], v[114:115]
	v_mov_b32_e32 v106, v18
	v_mov_b32_e32 v107, v22
	v_pk_fma_f32 v[110:111], v[112:113], v[112:113], v[110:111]
	v_mov_b32_e32 v108, v19
	v_mov_b32_e32 v109, v23
	v_pk_fma_f32 v[106:107], v[106:107], v[106:107], v[110:111]
	v_mov_b32_e32 v8, v100
	v_mov_b32_e32 v9, v86
	v_pk_fma_f32 v[106:107], v[108:109], v[108:109], v[106:107]
	v_mov_b32_e32 v104, v101
	v_mov_b32_e32 v105, v87
	v_pk_fma_f32 v[8:9], v[8:9], v[8:9], v[106:107]
	s_nop 0
	v_pk_fma_f32 v[8:9], v[104:105], v[104:105], v[8:9]
	s_nop 0
	v_add_f32_e32 v8, v8, v9
	v_add_f32_e32 v8, v8, v16
	v_add_f32_e32 v8, v8, v17
	ds_bpermute_b32 v9, v198, v8
	s_waitcnt lgkmcnt(0)
; __device__ __forceinline__ unsigned pk2(float lo, float hi) { f32x2_t v = {lo, hi}; bf16x2_t b = __builtin_convertvector(v, bf16x2_t); return __builtin_bit_cast(unsigned, b); }
; __device__ __forceinline__ float bflo(unsigned u) { return __uint_as_float(u << 16); }
; __device__ __forceinline__ float bfhi(unsigned u) { return __uint_as_float(u & 0xffff0000u); }
; __device__ __forceinline__ float frsq(float x) { return __builtin_amdgcn_rsqf(x); }
; __device__ __forceinline__ void mem_unit(const Args& a, int l, LAS unsigned char* lds, int b, int hm, int qb) {
;     ...
;         for (int ks = 0; ks < 4; ++ks) { u[ks] = *(const u32x4*)(proj + (rowbase + q0 + qt * 16 + fr) * NCOL + CQM + hm * 128 + ks * 32 + fq * 8);
;             ss += bflo(u[ks].x) * bflo(u[ks].x) + bfhi(u[ks].x) * bfhi(u[ks].x) + bflo(u[ks].y) * bflo(u[ks].y) + bfhi(u[ks].y) * bfhi(u[ks].y)
;                 + bflo(u[ks].z) * bflo(u[ks].z) + bfhi(u[ks].z) * bfhi(u[ks].z) + bflo(u[ks].w) * bflo(u[ks].w) + bfhi(u[ks].w) * bfhi(u[ks].w); }
;         ss += __shfl_xor(ss, 16); ss += __shfl_xor(ss, 32);
;         const float r = frsq(ss * (1.f / 128.f) + EPS) * (0.08838834764831845f * LOG2E);
; #pragma unroll
;         for (int ks = 0; ks < 4; ++ks) { const float* g = a.memqn + l * 128 + ks * 32 + fq * 8; const f32x4 g0 = *(const f32x4*)g, g1 = *(const f32x4*)(g + 4);
;             u32x4 o; o.x = pk2(bflo(u[ks].x) * r * g0.x, bfhi(u[ks].x) * r * g0.y); o.y = pk2(bflo(u[ks].y) * r * g0.z, bfhi(u[ks].y) * r * g0.w);
;             o.z = pk2(bflo(u[ks].z) * r * g1.x, bfhi(u[ks].z) * r * g1.y); o.w = pk2(bflo(u[ks].w) * r * g1.z, bfhi(u[ks].w) * r * g1.w);
;             qf[qt][ks] = __builtin_bit_cast(bf16x8, o); }
	v_add_f32_e32 v8, v8, v9
	ds_bpermute_b32 v9, v199, v8
	s_waitcnt lgkmcnt(0)
	v_add_f32_e32 v8, v8, v9
	v_fmamk_f32 v8, v8, 0x3c000000, v186
	v_rsq_f32_e32 v8, v8
	s_nop 0
	v_mul_f32_e32 v104, 0x3e0293ee, v8
	v_pk_mul_f32 v[8:9], v[104:105], v[102:103] op_sel_hi:[0,1]
	s_waitcnt vmcnt(6)
	v_pk_mul_f32 v[8:9], v[24:25], v[8:9]
	v_pk_mul_f32 v[74:75], v[104:105], v[74:75] op_sel_hi:[0,1]
	v_cvt_pk_bf16_f32 v16, v8, v9
	v_pk_mul_f32 v[8:9], v[104:105], v[10:11] op_sel_hi:[0,1]
	v_pk_mul_f32 v[8:9], v[26:27], v[8:9]
	v_pk_mul_f32 v[10:11], v[104:105], v[78:79] op_sel_hi:[0,1]
	v_cvt_pk_bf16_f32 v17, v8, v9
	v_pk_mul_f32 v[8:9], v[104:105], v[18:19] op_sel_hi:[0,1]
	v_pk_mul_f32 v[8:9], v[68:69], v[8:9]
	s_waitcnt vmcnt(0)
	v_pk_mul_f32 v[10:11], v[34:35], v[10:11]
	v_cvt_pk_bf16_f32 v18, v8, v9
	v_pk_mul_f32 v[8:9], v[104:105], v[100:101] op_sel_hi:[0,1]
	v_pk_mul_f32 v[8:9], v[70:71], v[8:9]
	v_pk_mul_f32 v[74:75], v[58:59], v[74:75]
	v_cvt_pk_bf16_f32 v19, v8, v9
	v_pk_mul_f32 v[8:9], v[104:105], v[20:21] op_sel_hi:[0,1]
	v_pk_mul_f32 v[8:9], v[28:29], v[8:9]
	s_nop 0
	v_cvt_pk_bf16_f32 v20, v8, v9
	v_pk_mul_f32 v[8:9], v[104:105], v[98:99] op_sel_hi:[0,1]
	v_pk_mul_f32 v[8:9], v[30:31], v[8:9]
	s_nop 0
	v_cvt_pk_bf16_f32 v21, v8, v9
	v_pk_mul_f32 v[8:9], v[104:105], v[22:23] op_sel_hi:[0,1]
	v_pk_mul_f32 v[8:9], v[64:65], v[8:9]
	s_nop 0
	v_cvt_pk_bf16_f32 v22, v8, v9
	v_pk_mul_f32 v[8:9], v[104:105], v[86:87] op_sel_hi:[0,1]
	v_pk_mul_f32 v[8:9], v[66:67], v[8:9]
	s_nop 0
	v_cvt_pk_bf16_f32 v23, v8, v9
	v_pk_mul_f32 v[8:9], v[104:105], v[12:13] op_sel_hi:[0,1]
	v_pk_mul_f32 v[8:9], v[36:37], v[8:9]
	s_nop 0
	v_cvt_pk_bf16_f32 v12, v8, v9
	v_pk_mul_f32 v[8:9], v[104:105], v[84:85] op_sel_hi:[0,1]
	v_pk_mul_f32 v[8:9], v[38:39], v[8:9]
	v_lshl_add_u64 v[84:85], v[156:157], 0, v[144:145]
	v_cvt_pk_bf16_f32 v13, v8, v9
	v_pk_mul_f32 v[8:9], v[104:105], v[14:15] op_sel_hi:[0,1]
	v_pk_mul_f32 v[8:9], v[60:61], v[8:9]
	s_nop 0
	v_cvt_pk_bf16_f32 v14, v8, v9
	v_pk_mul_f32 v[8:9], v[104:105], v[82:83] op_sel_hi:[0,1]
	v_pk_mul_f32 v[8:9], v[62:63], v[8:9]
	s_nop 0
	v_cvt_pk_bf16_f32 v15, v8, v9
	v_pk_mul_f32 v[8:9], v[104:105], v[80:81] op_sel_hi:[0,1]
	v_pk_mul_f32 v[8:9], v[32:33], v[8:9]
	s_nop 0
	v_cvt_pk_bf16_f32 v8, v8, v9
	v_cvt_pk_bf16_f32 v9, v10, v11
	v_pk_mul_f32 v[10:11], v[104:105], v[76:77] op_sel_hi:[0,1]
	v_pk_mul_f32 v[10:11], v[56:57], v[10:11]
	s_nop 0
	v_cvt_pk_bf16_f32 v10, v10, v11
	v_cvt_pk_bf16_f32 v11, v74, v75
	global_load_dwordx4 v[72:75], v[84:85], off offset:2048
	global_load_dwordx4 v[76:79], v[84:85], off offset:2112
	global_load_dwordx4 v[80:83], v[84:85], off offset:2176
	s_nop 0
	global_load_dwordx4 v[84:87], v[84:85], off offset:2240
	s_waitcnt vmcnt(1)
	v_and_b32_e32 v107, 0xffff0000, v80
	s_waitcnt vmcnt(0)
	v_and_b32_e32 v103, 0xffff0000, v84
	v_lshlrev_b32_e32 v102, 16, v84
	v_lshlrev_b32_e32 v106, 16, v80
	v_mov_b32_e32 v120, v107
	v_mov_b32_e32 v121, v103
	v_lshlrev_b32_e32 v100, 16, v86
	v_and_b32_e32 v101, 0xffff0000, v86
	v_lshlrev_b32_e32 v86, 16, v85
	v_lshlrev_b32_e32 v104, 16, v82
	v_and_b32_e32 v105, 0xffff0000, v82
	v_lshlrev_b32_e32 v82, 16, v81
	v_mov_b32_e32 v118, v106
	v_mov_b32_e32 v119, v102
	v_pk_mul_f32 v[120:121], v[120:121], v[120:121]
	v_lshlrev_b32_e32 v98, 16, v87
	v_and_b32_e32 v99, 0xffff0000, v87
	v_and_b32_e32 v87, 0xffff0000, v85
	v_lshlrev_b32_e32 v84, 16, v83
	v_and_b32_e32 v85, 0xffff0000, v83
	v_and_b32_e32 v83, 0xffff0000, v81
	v_mov_b32_e32 v114, v82
	v_mov_b32_e32 v115, v86
	v_pk_fma_f32 v[118:119], v[118:119], v[118:119], v[120:121]
	v_mov_b32_e32 v116, v83
	v_mov_b32_e32 v117, v87
	v_pk_fma_f32 v[114:115], v[114:115], v[114:115], v[118:119]
	v_mov_b32_e32 v110, v104
	v_mov_b32_e32 v111, v100
	v_pk_fma_f32 v[114:115], v[116:117], v[116:117], v[114:115]
	v_mov_b32_e32 v112, v105
	v_mov_b32_e32 v113, v101
	v_pk_fma_f32 v[110:111], v[110:111], v[110:111], v[114:115]
	v_and_b32_e32 v117, 0xffff0000, v72
	v_pk_fma_f32 v[110:111], v[112:113], v[112:113], v[110:111]
	v_and_b32_e32 v113, 0xffff0000, v76
	v_mov_b32_e32 v80, v84
	v_mov_b32_e32 v81, v98
	v_lshlrev_b32_e32 v112, 16, v76
	v_lshlrev_b32_e32 v116, 16, v72
	v_mov_b32_e32 v130, v117
	v_mov_b32_e32 v131, v113
	v_mov_b32_e32 v108, v85
	v_mov_b32_e32 v109, v99
	v_pk_fma_f32 v[80:81], v[80:81], v[80:81], v[110:111]
	v_lshlrev_b32_e32 v110, 16, v78
	v_and_b32_e32 v111, 0xffff0000, v78
	v_lshlrev_b32_e32 v78, 16, v77
	v_lshlrev_b32_e32 v114, 16, v74
	v_and_b32_e32 v115, 0xffff0000, v74
	v_lshlrev_b32_e32 v74, 16, v73
	v_mov_b32_e32 v128, v116
	v_mov_b32_e32 v129, v112
	v_pk_mul_f32 v[130:131], v[130:131], v[130:131]
	v_pk_fma_f32 v[80:81], v[108:109], v[108:109], v[80:81]
	v_lshlrev_b32_e32 v108, 16, v79
	v_and_b32_e32 v109, 0xffff0000, v79
	v_and_b32_e32 v79, 0xffff0000, v77
	v_lshlrev_b32_e32 v76, 16, v75
	v_and_b32_e32 v77, 0xffff0000, v75
	v_and_b32_e32 v75, 0xffff0000, v73
	v_mov_b32_e32 v124, v74
	v_mov_b32_e32 v125, v78
	v_pk_fma_f32 v[128:129], v[128:129], v[128:129], v[130:131]
	v_mov_b32_e32 v126, v75
	v_mov_b32_e32 v127, v79
	v_pk_fma_f32 v[124:125], v[124:125], v[124:125], v[128:129]
	v_mov_b32_e32 v120, v114
	v_mov_b32_e32 v121, v110
	v_pk_fma_f32 v[124:125], v[126:127], v[126:127], v[124:125]
	v_mov_b32_e32 v122, v115
	v_mov_b32_e32 v123, v111
	v_pk_fma_f32 v[120:121], v[120:121], v[120:121], v[124:125]
	v_mov_b32_e32 v72, v76
	v_mov_b32_e32 v73, v108
	v_pk_fma_f32 v[120:121], v[122:123], v[122:123], v[120:121]
	v_mov_b32_e32 v118, v77
	v_mov_b32_e32 v119, v109
	v_pk_fma_f32 v[72:73], v[72:73], v[72:73], v[120:121]
	s_nop 0
	v_pk_fma_f32 v[72:73], v[118:119], v[118:119], v[72:73]
	s_nop 0
	v_add_f32_e32 v72, v72, v73
	v_add_f32_e32 v72, v72, v80
	v_add_f32_e32 v72, v72, v81
	ds_bpermute_b32 v73, v198, v72
	s_waitcnt lgkmcnt(0)
; __device__ __forceinline__ unsigned pk2(float lo, float hi) { f32x2_t v = {lo, hi}; bf16x2_t b = __builtin_convertvector(v, bf16x2_t); return __builtin_bit_cast(unsigned, b); }
; __device__ __forceinline__ float bflo(unsigned u) { return __uint_as_float(u << 16); }
; __device__ __forceinline__ float bfhi(unsigned u) { return __uint_as_float(u & 0xffff0000u); }
; __device__ __forceinline__ void mem_unit(const Args& a, int l, LAS unsigned char* lds, int b, int hm, int qb) {
;     ...
;         for (int ks = 0; ks < 4; ++ks) { const float* g = a.memqn + l * 128 + ks * 32 + fq * 8; const f32x4 g0 = *(const f32x4*)g, g1 = *(const f32x4*)(g + 4);
;             u32x4 o; o.x = pk2(bflo(u[ks].x) * r * g0.x, bfhi(u[ks].x) * r * g0.y); o.y = pk2(bflo(u[ks].y) * r * g0.z, bfhi(u[ks].y) * r * g0.w);
;             o.z = pk2(bflo(u[ks].z) * r * g1.x, bfhi(u[ks].z) * r * g1.y); o.w = pk2(bflo(u[ks].w) * r * g1.z, bfhi(u[ks].w) * r * g1.w);
;             qf[qt][ks] = __builtin_bit_cast(bf16x8, o); }
;     ...
;     MEM_STORE(0);
	v_add_f32_e32 v72, v72, v73
	ds_bpermute_b32 v73, v199, v72
	s_waitcnt lgkmcnt(0)
	v_add_f32_e32 v72, v72, v73
	v_fmamk_f32 v72, v72, 0x3c000000, v186
	v_rsq_f32_e32 v72, v72
	s_nop 0
	v_mul_f32_e32 v72, 0x3e0293ee, v72
	v_pk_mul_f32 v[80:81], v[72:73], v[116:117] op_sel_hi:[0,1]
	v_pk_mul_f32 v[74:75], v[72:73], v[74:75] op_sel_hi:[0,1]
	v_pk_mul_f32 v[24:25], v[24:25], v[80:81]
	v_pk_mul_f32 v[26:27], v[26:27], v[74:75]
	v_cvt_pk_bf16_f32 v24, v24, v25
	v_cvt_pk_bf16_f32 v25, v26, v27
	v_pk_mul_f32 v[26:27], v[72:73], v[114:115] op_sel_hi:[0,1]
	v_pk_mul_f32 v[26:27], v[68:69], v[26:27]
	v_pk_mul_f32 v[68:69], v[72:73], v[76:77] op_sel_hi:[0,1]
	v_pk_mul_f32 v[68:69], v[70:71], v[68:69]
	v_cvt_pk_bf16_f32 v26, v26, v27
	v_cvt_pk_bf16_f32 v27, v68, v69
	v_pk_mul_f32 v[68:69], v[72:73], v[112:113] op_sel_hi:[0,1]
	v_pk_mul_f32 v[28:29], v[28:29], v[68:69]
	v_pk_mul_f32 v[68:69], v[72:73], v[78:79] op_sel_hi:[0,1]
	v_pk_mul_f32 v[30:31], v[30:31], v[68:69]
	v_cvt_pk_bf16_f32 v28, v28, v29
	v_cvt_pk_bf16_f32 v29, v30, v31
	v_pk_mul_f32 v[30:31], v[72:73], v[110:111] op_sel_hi:[0,1]
	v_pk_mul_f32 v[30:31], v[64:65], v[30:31]
	v_pk_mul_f32 v[64:65], v[72:73], v[108:109] op_sel_hi:[0,1]
	v_pk_mul_f32 v[64:65], v[66:67], v[64:65]
	v_cvt_pk_bf16_f32 v30, v30, v31
	v_cvt_pk_bf16_f32 v31, v64, v65
	v_pk_mul_f32 v[64:65], v[72:73], v[106:107] op_sel_hi:[0,1]
	v_pk_mul_f32 v[36:37], v[36:37], v[64:65]
	v_pk_mul_f32 v[64:65], v[72:73], v[82:83] op_sel_hi:[0,1]
	v_pk_mul_f32 v[38:39], v[38:39], v[64:65]
	v_cvt_pk_bf16_f32 v36, v36, v37
	v_cvt_pk_bf16_f32 v37, v38, v39
	v_pk_mul_f32 v[38:39], v[72:73], v[104:105] op_sel_hi:[0,1]
	v_pk_mul_f32 v[38:39], v[60:61], v[38:39]
	v_pk_mul_f32 v[60:61], v[72:73], v[84:85] op_sel_hi:[0,1]
	v_pk_mul_f32 v[60:61], v[62:63], v[60:61]
	v_cvt_pk_bf16_f32 v38, v38, v39
	v_cvt_pk_bf16_f32 v39, v60, v61
	v_pk_mul_f32 v[60:61], v[72:73], v[102:103] op_sel_hi:[0,1]
	v_pk_mul_f32 v[32:33], v[32:33], v[60:61]
	v_pk_mul_f32 v[60:61], v[72:73], v[86:87] op_sel_hi:[0,1]
	v_pk_mul_f32 v[34:35], v[34:35], v[60:61]
	v_cvt_pk_bf16_f32 v32, v32, v33
	v_cvt_pk_bf16_f32 v33, v34, v35
	v_pk_mul_f32 v[34:35], v[72:73], v[100:101] op_sel_hi:[0,1]
	v_pk_mul_f32 v[34:35], v[56:57], v[34:35]
	v_pk_mul_f32 v[56:57], v[72:73], v[98:99] op_sel_hi:[0,1]
	v_pk_mul_f32 v[56:57], v[58:59], v[56:57]
	v_lshlrev_b32_e32 v66, 16, v52
	v_and_b32_e32 v67, 0xffff0000, v52
	v_cvt_pk_bf16_f32 v34, v34, v35
	v_cvt_pk_bf16_f32 v35, v56, v57
	v_mov_b32_e32 v56, s5
	v_lshlrev_b32_e32 v62, 16, v53
	v_and_b32_e32 v63, 0xffff0000, v53
	v_pk_mul_f32 v[52:53], v[66:67], v[66:67]
	ds_read_b32 v68, v56
	v_lshlrev_b32_e32 v56, 4, v96
	v_pk_mul_f32 v[64:65], v[62:63], v[62:63]
	v_add_f32_e32 v52, v52, v53
	v_and_b32_e32 v56, 0xf0, v56
	v_lshlrev_b32_e32 v60, 16, v54
	v_and_b32_e32 v61, 0xffff0000, v54
	v_add_f32_e32 v52, v64, v52
	v_add_u32_e32 v173, 0, v56
	v_lshlrev_b32_e32 v56, 16, v55
	v_and_b32_e32 v57, 0xffff0000, v55
	v_pk_mul_f32 v[54:55], v[60:61], v[60:61]
	v_add_f32_e32 v52, v65, v52
	v_add_f32_e32 v52, v54, v52
	v_pk_mul_f32 v[58:59], v[56:57], v[56:57]
	v_add_f32_e32 v52, v55, v52
	v_add_f32_e32 v52, v58, v52
	v_add_f32_e32 v52, v59, v52
	s_nop 1
	v_mov_b32_dpp v53, v52 quad_perm:[1,0,3,2] row_mask:0xf bank_mask:0xf
	s_waitcnt lgkmcnt(1)
	v_xor_b32_e32 v72, 0x80000000, v68
	v_mov_b32_e32 v108, 0
	v_mov_b32_e32 v73, v72
	v_mov_b32_e32 v74, v72
	s_waitcnt lgkmcnt(0)
	v_add_f32_e32 v52, v52, v53
	s_nop 1
	v_mov_b32_dpp v53, v52 quad_perm:[2,3,0,1] row_mask:0xf bank_mask:0xf
	v_mov_b32_e32 v75, v72
	v_mov_b32_e32 v109, v108
	v_mov_b32_e32 v110, v108
	v_mov_b32_e32 v111, v108
	s_waitcnt lgkmcnt(0)
	v_add_f32_e32 v52, v52, v53
	s_nop 1
	v_mov_b32_dpp v53, v52 row_half_mirror row_mask:0xf bank_mask:0xf
	v_mov_b32_e32 v112, v108
	v_mov_b32_e32 v113, v108
	v_mov_b32_e32 v114, v108
	v_mov_b32_e32 v115, v108
	s_waitcnt lgkmcnt(0)
	v_add_f32_e32 v52, v52, v53
	s_nop 1
	v_mov_b32_dpp v53, v52 row_mirror row_mask:0xf bank_mask:0xf
	v_mov_b32_e32 v84, v108
	v_mov_b32_e32 v85, v108
	v_mov_b32_e32 v86, v108
	v_mov_b32_e32 v87, v108
	s_waitcnt lgkmcnt(0)
	v_add_f32_e32 v52, v52, v53
	v_fmamk_f32 v52, v52, 0x3c000000, v186
	v_rsq_f32_e32 v58, v52
	v_mov_b32_e32 v92, v108
	v_mov_b32_e32 v94, v108
	v_mov_b32_e32 v97, v108
	v_pk_mul_f32 v[52:53], v[58:59], v[66:67] op_sel_hi:[0,1]
	v_pk_mul_f32 v[54:55], v[58:59], v[62:63] op_sel_hi:[0,1]
	v_pk_mul_f32 v[52:53], v[4:5], v[52:53]
	v_pk_mul_f32 v[54:55], v[6:7], v[54:55]
	v_cvt_pk_bf16_f32 v52, v52, v53
	v_cvt_pk_bf16_f32 v53, v54, v55
	v_pk_mul_f32 v[54:55], v[58:59], v[60:61] op_sel_hi:[0,1]
	v_pk_mul_f32 v[56:57], v[58:59], v[56:57] op_sel_hi:[0,1]
	v_pk_mul_f32 v[54:55], v[0:1], v[54:55]
	v_pk_mul_f32 v[56:57], v[2:3], v[56:57]
	v_cvt_pk_bf16_f32 v54, v54, v55
	v_cvt_pk_bf16_f32 v55, v56, v57
	v_add_u32_e32 v56, v173, v174
	v_lshlrev_b32_e32 v58, 16, v44
	v_and_b32_e32 v59, 0xffff0000, v44
	ds_write_b128 v56, v[52:55]
	v_lshlrev_b32_e32 v54, 16, v45
	v_and_b32_e32 v55, 0xffff0000, v45
	v_pk_mul_f32 v[44:45], v[58:59], v[58:59]
	v_add_u32_e32 v52, v173, v175
	v_pk_mul_f32 v[56:57], v[54:55], v[54:55]
	v_add_f32_e32 v44, v44, v45
	ds_write_b128 v52, v[48:51] offset:17408
	v_lshlrev_b32_e32 v52, 16, v46
	v_and_b32_e32 v53, 0xffff0000, v46
	v_add_f32_e32 v44, v56, v44
	v_lshlrev_b32_e32 v48, 16, v47
	v_and_b32_e32 v49, 0xffff0000, v47
	v_pk_mul_f32 v[46:47], v[52:53], v[52:53]
	v_add_f32_e32 v44, v57, v44
	v_add_f32_e32 v44, v46, v44
	v_pk_mul_f32 v[50:51], v[48:49], v[48:49]
	v_add_f32_e32 v44, v47, v44
	v_add_f32_e32 v44, v50, v44
	v_add_f32_e32 v44, v51, v44
	s_nop 1
	v_mov_b32_dpp v45, v44 quad_perm:[1,0,3,2] row_mask:0xf bank_mask:0xf
	v_mov_b32_e32 v98, v108
	v_mov_b32_e32 v99, v108
	v_mov_b32_e32 v76, v108
	v_mov_b32_e32 v77, v108
	s_waitcnt lgkmcnt(0)
; #define LAS __attribute__((address_space(3)))
; #define MFMA16(a, b, c) __builtin_amdgcn_mfma_f32_16x16x32_bf16((a), (b), (c), 0, 0, 0)
; #define BAR_LDS() do { asm volatile("s_waitcnt lgkmcnt(0)" ::: "memory"); __builtin_amdgcn_s_barrier(); asm volatile("" ::: "memory"); } while (0)
; #define MEM_LOAD(kt) do { _Pragma("unroll") for (int ii = 0; ii < 2; ++ii) { const int cid = tid + 512 * ii; \
;         ukr[ii] = *(const u32x4*)(kvm + (size_t)((kt) * 64 + (cid >> 4)) * 1024 + hm * 128 + (cid & 15) * 8); \
;         uvr[ii] = *(const u32x4*)(kvm + (size_t)((kt) * 64 + (cid >> 4)) * 1024 + 512 + hm * 128 + (cid & 15) * 8); } } while (0)
; template <int D, int QT0>
; __device__ __forceinline__ void qk_tile(const LAS unsigned char* Ks, int KP, const bf16x8 (&qf)[2][D / 32], f32x4 (&s)[4][2], int fr, int fq, float b0, float b1) {
; #pragma unroll
;     for (int a = 0; a < 4; ++a) { s[a][0] = (f32x4){b0, b0, b0, b0}; s[a][1] = (f32x4){b1, b1, b1, b1}; }
; #pragma unroll
;     for (int a = 0; a < 4; ++a)
; #pragma unroll
;         for (int ks = 0; ks < D / 32; ++ks) { const bf16x8 kfr = *(const LAS bf16x8*)(Ks + (a * 16 + fr) * KP + (ks * 32 + fq * 8) * 2);
;             if (QT0 == 0) s[a][0] = MFMA16(kfr, qf[0][ks], s[a][0]);
;             s[a][1] = MFMA16(kfr, qf[1][ks], s[a][1]); }
; }
; __device__ __forceinline__ void mem_unit(const Args& a, int l, LAS unsigned char* lds, int b, int hm, int qb) {
;     ...
;     MEM_STORE(0);
;     BAR_LDS();
;     for (int kt = 0; kt < 4; ++kt) {
;         if (kt < 3) MEM_LOAD(kt + 1);
;         attn_tile<128, false, 0>(Ks + (kt & 1) * 35840, 272, Vs + (kt & 1) * 35840, 288, qf, o, ol, fr, fq, 0, 0, 0, -gm, -gm);
	v_add_f32_e32 v44, v44, v45
	s_nop 1
	v_mov_b32_dpp v45, v44 quad_perm:[2,3,0,1] row_mask:0xf bank_mask:0xf
	v_mov_b32_e32 v78, v108
	v_mov_b32_e32 v79, v108
	v_mov_b32_e32 v80, v108
	v_mov_b32_e32 v81, v108
	s_waitcnt lgkmcnt(0)
	v_add_f32_e32 v44, v44, v45
	s_nop 1
	v_mov_b32_dpp v45, v44 row_half_mirror row_mask:0xf bank_mask:0xf
	v_mov_b32_e32 v82, v108
	v_mov_b32_e32 v83, v108
	v_mov_b32_e32 v100, v108
	v_mov_b32_e32 v101, v108
	s_waitcnt lgkmcnt(0)
	v_add_f32_e32 v44, v44, v45
	s_nop 1
	v_mov_b32_dpp v45, v44 row_mirror row_mask:0xf bank_mask:0xf
	v_mov_b32_e32 v102, v108
	v_mov_b32_e32 v103, v108
	v_mov_b32_e32 v104, v108
	v_mov_b32_e32 v105, v108
	s_waitcnt lgkmcnt(0)
	v_add_f32_e32 v44, v44, v45
	v_fmamk_f32 v44, v44, 0x3c000000, v186
	v_rsq_f32_e32 v50, v44
	v_mov_b32_e32 v106, v108
	v_mov_b32_e32 v107, v108
	v_mov_b32_e32 v64, v108
	v_pk_mul_f32 v[44:45], v[50:51], v[58:59] op_sel_hi:[0,1]
	v_pk_mul_f32 v[46:47], v[50:51], v[54:55] op_sel_hi:[0,1]
	v_pk_mul_f32 v[44:45], v[4:5], v[44:45]
	v_pk_mul_f32 v[46:47], v[6:7], v[46:47]
	v_cvt_pk_bf16_f32 v44, v44, v45
	v_cvt_pk_bf16_f32 v45, v46, v47
	v_pk_mul_f32 v[46:47], v[50:51], v[52:53] op_sel_hi:[0,1]
	v_pk_mul_f32 v[48:49], v[50:51], v[48:49] op_sel_hi:[0,1]
	v_pk_mul_f32 v[46:47], v[0:1], v[46:47]
	v_pk_mul_f32 v[48:49], v[2:3], v[48:49]
	v_cvt_pk_bf16_f32 v46, v46, v47
	v_cvt_pk_bf16_f32 v47, v48, v49
	v_add_u32_e32 v48, v173, v177
	ds_write_b128 v48, v[44:47]
	v_add_u32_e32 v44, v173, v180
	ds_write_b128 v44, v[40:43] offset:17408
	v_mul_u32_u24_e32 v40, 0x110, v93
	v_add3_u32 v176, 0, v144, v40
	v_lshlrev_b32_e32 v144, 2, v95
	v_bfe_u32 v40, v96, 2, 2
	v_lshlrev_b32_e32 v41, 3, v93
	v_or_b32_e32 v40, v144, v40
	v_and_b32_e32 v170, 24, v41
	v_mad_u32_u24 v172, v40, s27, 0
	v_or_b32_e32 v169, 0x60, v41
	v_or_b32_e32 v168, 0xe0, v41
	v_lshl_add_u64 v[40:41], s[40:41], 0, v[90:91]
	v_lshlrev_b32_e32 v42, 4, v93
	v_or3_b32 v40, v40, s4, v42
	s_waitcnt lgkmcnt(0)
	s_barrier
	v_lshl_add_u64 v[164:165], s[78:79], 0, v[40:41]
	v_lshl_add_u64 v[40:41], s[40:41], 0, v[88:89]
	v_or3_b32 v40, v40, s4, v42
	v_lshl_add_u64 v[166:167], s[78:79], 0, v[40:41]
	v_mov_b32_e32 v88, v108
	v_mov_b32_e32 v89, v108
	v_mov_b32_e32 v90, v108
	v_mov_b32_e32 v91, v108
	v_mov_b32_e32 v93, v108
	v_mov_b32_e32 v95, v108
	v_mov_b32_e32 v96, v108
	v_mov_b32_e32 v65, v108
	v_mov_b32_e32 v66, v108
	v_mov_b32_e32 v67, v108
	v_mov_b32_e32 v68, v108
	v_mov_b32_e32 v69, v108
	v_mov_b32_e32 v70, v108
	v_mov_b32_e32 v71, v108
	v_mov_b32_e32 v56, v108
	v_mov_b32_e32 v57, v108
	v_mov_b32_e32 v58, v108
	v_mov_b32_e32 v59, v108
	v_mov_b32_e32 v60, v108
	v_mov_b32_e32 v61, v108
	v_mov_b32_e32 v62, v108
	v_mov_b32_e32 v63, v108
	v_mov_b32_e32 v48, v108
	v_mov_b32_e32 v49, v108
	v_mov_b32_e32 v50, v108
	v_mov_b32_e32 v51, v108
	v_mov_b32_e32 v52, v108
	v_mov_b32_e32 v53, v108
	v_mov_b32_e32 v54, v108
	v_mov_b32_e32 v55, v108
	v_mov_b32_e32 v40, v108
	v_mov_b32_e32 v41, v108
	v_mov_b32_e32 v42, v108
	v_mov_b32_e32 v43, v108
	v_mov_b32_e32 v44, v108
	v_mov_b32_e32 v45, v108
	v_mov_b32_e32 v46, v108
	v_mov_b32_e32 v47, v108
.LBB0_520:
	v_lshl_add_u64 v[116:117], v[166:167], 0, s[46:47]
	v_add_co_u32_e32 v116, vcc, s34, v116
	s_bitcmp1_b32 s6, 0
	s_nop 0
	v_addc_co_u32_e32 v117, vcc, 0, v117, vcc
	global_load_dwordx4 v[128:131], v[116:117], off
	global_load_dwordx4 v[124:127], v[116:117], off offset:1024
	v_lshl_add_u64 v[116:117], v[164:165], 0, s[46:47]
	v_add_co_u32_e32 v116, vcc, s34, v116
	s_cselect_b32 s4, 0x8c00, 0
	s_nop 0
	v_addc_co_u32_e32 v117, vcc, 0, v117, vcc
	v_add_u32_e32 v181, s4, v176
	global_load_dwordx4 v[120:123], v[116:117], off
	s_nop 0
	global_load_dwordx4 v[116:119], v[116:117], off offset:1024
	ds_read_b128 v[132:135], v181
	ds_read_b128 v[140:143], v181 offset:64
	s_waitcnt lgkmcnt(1)
	v_mfma_f32_16x16x32_bf16 v[136:139], v[132:135], v[16:19], v[72:75]
	ds_read_b128 v[204:207], v181 offset:4416
	s_mov_b32 s70, s68
	s_mov_b32 s71, s68
	v_mfma_f32_16x16x32_bf16 v[132:135], v[132:135], v[24:27], v[72:75]
	ds_read_b128 v[212:215], v181 offset:8768
	s_mov_b32 s69, s68
	ds_read_b128 v[220:223], v181 offset:13120
	s_waitcnt lgkmcnt(3)
	v_mfma_f32_16x16x32_bf16 v[136:139], v[140:143], v[20:23], v[136:139]
	v_mfma_f32_16x16x32_bf16 v[132:135], v[140:143], v[28:31], v[132:135]
	ds_read_b128 v[140:143], v181 offset:128
	s_waitcnt lgkmcnt(0)
	v_mfma_f32_16x16x32_bf16 v[136:139], v[140:143], v[12:15], v[136:139]
	v_mfma_f32_16x16x32_bf16 v[132:135], v[140:143], v[36:39], v[132:135]
	ds_read_b128 v[140:143], v181 offset:192
	s_waitcnt lgkmcnt(0)
	v_mfma_f32_16x16x32_bf16 v[136:139], v[140:143], v[8:11], v[136:139]
	s_nop 7
	v_exp_f32_e32 v136, v136
	v_mfma_f32_16x16x32_bf16 v[132:135], v[140:143], v[32:35], v[132:135]
	ds_read_b128 v[140:143], v181 offset:4352
	v_exp_f32_e32 v137, v137
	v_exp_f32_e32 v138, v138
	s_waitcnt lgkmcnt(0)
	v_mfma_f32_16x16x32_bf16 v[200:203], v[140:143], v[16:19], v[72:75]
	v_exp_f32_e32 v139, v139
	v_mfma_f32_16x16x32_bf16 v[140:143], v[140:143], v[24:27], v[72:75]
	v_mfma_f32_16x16x32_bf16 v[200:203], v[204:207], v[20:23], v[200:203]
	v_mfma_f32_16x16x32_bf16 v[140:143], v[204:207], v[28:31], v[140:143]
	ds_read_b128 v[204:207], v181 offset:4480
	s_waitcnt lgkmcnt(0)
	v_mfma_f32_16x16x32_bf16 v[200:203], v[204:207], v[12:15], v[200:203]
	v_mfma_f32_16x16x32_bf16 v[140:143], v[204:207], v[36:39], v[140:143]
	ds_read_b128 v[204:207], v181 offset:4544
	s_waitcnt lgkmcnt(0)
	v_mfma_f32_16x16x32_bf16 v[200:203], v[204:207], v[8:11], v[200:203]
	s_nop 7
	v_exp_f32_e32 v225, v201
	v_mfma_f32_16x16x32_bf16 v[140:143], v[204:207], v[32:35], v[140:143]
	ds_read_b128 v[204:207], v181 offset:8704
	v_exp_f32_e32 v226, v202
	v_exp_f32_e32 v227, v203
	s_waitcnt lgkmcnt(0)
; #define LAS __attribute__((address_space(3)))
; __device__ __forceinline__ unsigned pk2(float lo, float hi) { f32x2_t v = {lo, hi}; bf16x2_t b = __builtin_convertvector(v, bf16x2_t); return __builtin_bit_cast(unsigned, b); }
; __device__ __forceinline__ float ex2(float x) { return __builtin_amdgcn_exp2f(x); }
; #define MFMA16(a, b, c) __builtin_amdgcn_mfma_f32_16x16x32_bf16((a), (b), (c), 0, 0, 0)
; template <int D, bool DIAG, int QT0>
; __device__ __forceinline__ void sm_pv_tile(f32x4 (&s)[4][2], const LAS unsigned char* Vs, int VP, f32x4 (&o)[D / 16][2], f32x4 (&ol)[2], int fr, int fq, int keyl0, int qla, int qlb) {
; #pragma unroll
;     for (int qt = QT0; qt < 2; ++qt) {
;         if (DIAG) {
;             const int ql = (qt == 0 ? qla : qlb) + fr - keyl0 - fq * 4;
; #pragma unroll
;             for (int a = 0; a < 4; ++a)
; #pragma unroll
;                 for (int jj = 0; jj < 4; ++jj) s[a][qt][jj] = (a * 16 + jj > ql) ? -1e30f : s[a][qt][jj];
;         }
; #pragma unroll
;         for (int a = 0; a < 4; ++a)
; #pragma unroll
;             for (int jj = 0; jj < 4; ++jj) s[a][qt][jj] = ex2(s[a][qt][jj]);
;     }
; #pragma unroll
;     for (int kst = 0; kst < 2; ++kst) {
;         bf16x8 pb[2];
; #pragma unroll
;         for (int qt = QT0; qt < 2; ++qt) { u32x4 pw; pw.x = pk2(s[2 * kst][qt][0], s[2 * kst][qt][1]); pw.y = pk2(s[2 * kst][qt][2], s[2 * kst][qt][3]);
;             pw.z = pk2(s[2 * kst + 1][qt][0], s[2 * kst + 1][qt][1]); pw.w = pk2(s[2 * kst + 1][qt][2], s[2 * kst + 1][qt][3]); pb[qt] = __builtin_bit_cast(bf16x8, pw); }
;         if (QT0 == 0) ol[0] = MFMA16(ONES8, pb[0], ol[0]);
;         ol[1] = MFMA16(ONES8, pb[1], ol[1]);
; #pragma unroll
;         for (int dt = 0; dt < D / 16; ++dt) { const s16x4 lo = tr4(Vs, VP, kst * 32 + fq * 4, dt * 16, fr), hi = tr4(Vs, VP, kst * 32 + 16 + fq * 4, dt * 16, fr);
;             const bf16x8 vf = __builtin_shufflevector(lo, hi, 0, 1, 2, 3, 4, 5, 6, 7);
;             if (QT0 == 0) o[dt][0] = MFMA16(vf, pb[0], o[dt][0]);
;             o[dt][1] = MFMA16(vf, pb[1], o[dt][1]); }
;     }
	v_mfma_f32_16x16x32_bf16 v[208:211], v[204:207], v[16:19], v[72:75]
	v_exp_f32_e32 v224, v200
	s_nop 1
	v_exp_f32_e32 v140, v140
	v_exp_f32_e32 v141, v141
	v_mfma_f32_16x16x32_bf16 v[204:207], v[204:207], v[24:27], v[72:75]
	v_exp_f32_e32 v142, v142
	v_exp_f32_e32 v143, v143
	v_mfma_f32_16x16x32_bf16 v[208:211], v[212:215], v[20:23], v[208:211]
	v_mfma_f32_16x16x32_bf16 v[204:207], v[212:215], v[28:31], v[204:207]
	ds_read_b128 v[212:215], v181 offset:8832
	s_waitcnt lgkmcnt(0)
	v_mfma_f32_16x16x32_bf16 v[208:211], v[212:215], v[12:15], v[208:211]
	v_mfma_f32_16x16x32_bf16 v[204:207], v[212:215], v[36:39], v[204:207]
	ds_read_b128 v[212:215], v181 offset:8896
	s_waitcnt lgkmcnt(0)
	v_mfma_f32_16x16x32_bf16 v[208:211], v[212:215], v[8:11], v[208:211]
	s_nop 7
	v_exp_f32_e32 v200, v211
	v_mfma_f32_16x16x32_bf16 v[212:215], v[212:215], v[32:35], v[204:207]
	v_exp_f32_e32 v182, v209
	v_exp_f32_e32 v183, v210
	s_nop 0
	ds_read_b128 v[204:207], v181 offset:13056
	s_waitcnt lgkmcnt(0)
	v_mfma_f32_16x16x32_bf16 v[216:219], v[204:207], v[16:19], v[72:75]
	v_mfma_f32_16x16x32_bf16 v[204:207], v[204:207], v[24:27], v[72:75]
	v_mfma_f32_16x16x32_bf16 v[216:219], v[220:223], v[20:23], v[216:219]
	v_mfma_f32_16x16x32_bf16 v[204:207], v[220:223], v[28:31], v[204:207]
	ds_read_b128 v[220:223], v181 offset:13184
	s_waitcnt lgkmcnt(0)
	v_mfma_f32_16x16x32_bf16 v[216:219], v[220:223], v[12:15], v[216:219]
	v_mfma_f32_16x16x32_bf16 v[204:207], v[220:223], v[36:39], v[204:207]
	ds_read_b128 v[220:223], v181 offset:13248
	v_exp_f32_e32 v181, v208
	v_exp_f32_e32 v208, v215
	s_waitcnt lgkmcnt(0)
	v_mfma_f32_16x16x32_bf16 v[216:219], v[220:223], v[8:11], v[216:219]
	s_nop 7
	v_exp_f32_e32 v201, v216
	v_mfma_f32_16x16x32_bf16 v[220:223], v[220:223], v[32:35], v[204:207]
	v_exp_f32_e32 v202, v217
	v_exp_f32_e32 v203, v218
	v_exp_f32_e32 v216, v132
	v_exp_f32_e32 v204, v219
	v_exp_f32_e32 v217, v133
	v_exp_f32_e32 v218, v134
	v_exp_f32_e32 v219, v135
	v_exp_f32_e32 v206, v213
	v_add_u32_e32 v213, s4, v172
	v_exp_f32_e32 v211, v222
	v_add_u32_e32 v222, v213, v170
	v_exp_f32_e32 v207, v214
	v_exp_f32_e32 v209, v220
	v_exp_f32_e32 v210, v221
	v_cvt_pk_bf16_f32 v132, v136, v137
	v_cvt_pk_bf16_f32 v136, v216, v217
	v_cvt_pk_bf16_f32 v137, v218, v219
	ds_read_b64_tr_b16 v[216:217], v222 offset:22016
	ds_read_b64_tr_b16 v[214:215], v222 offset:17408
	ds_read_b64_tr_b16 v[218:219], v222 offset:17440
	ds_read_b64_tr_b16 v[220:221], v222 offset:22048
	v_cvt_pk_bf16_f32 v133, v138, v139
	v_cvt_pk_bf16_f32 v134, v224, v225
	v_cvt_pk_bf16_f32 v135, v226, v227
	v_cvt_pk_bf16_f32 v138, v140, v141
	v_cvt_pk_bf16_f32 v139, v142, v143
	s_waitcnt lgkmcnt(2)
	v_mfma_f32_16x16x32_bf16 v[84:87], v[214:217], v[132:135], v[84:87]
	v_mov_b64_e32 v[142:143], s[70:71]
	v_mov_b64_e32 v[140:141], s[68:69]
	v_exp_f32_e32 v205, v212
	v_mfma_f32_16x16x32_bf16 v[88:91], v[214:217], v[136:139], v[88:91]
	ds_read_b64_tr_b16 v[214:215], v222 offset:17472
	ds_read_b64_tr_b16 v[216:217], v222 offset:22080
	v_exp_f32_e32 v212, v223
	s_andn2_b32 s4, 1, s6
	s_waitcnt lgkmcnt(2)
	v_mfma_f32_16x16x32_bf16 v[92:95], v[218:221], v[132:135], v[92:95]
	s_mul_i32 s4, s4, 0x8c00
	s_add_i32 s6, s6, 1
	s_add_u32 s46, s46, 0x20000
	v_mfma_f32_16x16x32_bf16 v[96:99], v[218:221], v[136:139], v[96:99]
	v_add_u32_e32 v218, v213, v169
	v_add_u32_e32 v213, v213, v168
	s_addc_u32 s47, s47, 0
	s_waitcnt lgkmcnt(0)
	v_mfma_f32_16x16x32_bf16 v[76:79], v[214:217], v[132:135], v[76:79]
	s_cmp_lg_u32 s46, 0x60000
	v_mfma_f32_16x16x32_bf16 v[80:83], v[214:217], v[136:139], v[80:83]
	ds_read_b64_tr_b16 v[214:215], v218 offset:17408
	ds_read_b64_tr_b16 v[216:217], v218 offset:22016
	s_waitcnt lgkmcnt(0)
	v_mfma_f32_16x16x32_bf16 v[100:103], v[214:217], v[132:135], v[100:103]
	v_mfma_f32_16x16x32_bf16 v[104:107], v[214:217], v[136:139], v[104:107]
	ds_read_b64_tr_b16 v[214:215], v222 offset:17536
	ds_read_b64_tr_b16 v[216:217], v222 offset:22144
	s_waitcnt lgkmcnt(0)
	v_mfma_f32_16x16x32_bf16 v[64:67], v[214:217], v[132:135], v[64:67]
	v_mfma_f32_16x16x32_bf16 v[68:71], v[214:217], v[136:139], v[68:71]
	ds_read_b64_tr_b16 v[214:215], v222 offset:17568
	ds_read_b64_tr_b16 v[216:217], v222 offset:22176
	s_waitcnt lgkmcnt(0)
	v_mfma_f32_16x16x32_bf16 v[56:59], v[214:217], v[132:135], v[56:59]
	v_mfma_f32_16x16x32_bf16 v[60:63], v[214:217], v[136:139], v[60:63]
	ds_read_b64_tr_b16 v[214:215], v222 offset:17600
	ds_read_b64_tr_b16 v[216:217], v222 offset:22208
	s_waitcnt lgkmcnt(0)
	v_mfma_f32_16x16x32_bf16 v[48:51], v[214:217], v[132:135], v[48:51]
	v_mfma_f32_16x16x32_bf16 v[52:55], v[214:217], v[136:139], v[52:55]
	ds_read_b64_tr_b16 v[214:215], v213 offset:17408
	ds_read_b64_tr_b16 v[216:217], v213 offset:22016
	v_mfma_f32_16x16x32_bf16 v[108:111], v[140:143], v[132:135], v[108:111]
	v_mfma_f32_16x16x32_bf16 v[112:115], v[140:143], v[136:139], v[112:115]
	s_waitcnt lgkmcnt(0)
	v_mfma_f32_16x16x32_bf16 v[40:43], v[214:217], v[132:135], v[40:43]
	v_cvt_pk_bf16_f32 v132, v181, v182
	v_cvt_pk_bf16_f32 v133, v183, v200
	v_cvt_pk_bf16_f32 v134, v201, v202
	v_mfma_f32_16x16x32_bf16 v[44:47], v[214:217], v[136:139], v[44:47]
	v_cvt_pk_bf16_f32 v135, v203, v204
	v_cvt_pk_bf16_f32 v136, v205, v206
	v_cvt_pk_bf16_f32 v137, v207, v208
	v_cvt_pk_bf16_f32 v138, v209, v210
	v_cvt_pk_bf16_f32 v139, v211, v212
	v_mfma_f32_16x16x32_bf16 v[108:111], v[140:143], v[132:135], v[108:111]
	v_add_u32_e32 v181, s4, v173
	v_mfma_f32_16x16x32_bf16 v[112:115], v[140:143], v[136:139], v[112:115]
	ds_read_b64_tr_b16 v[140:141], v222 offset:26624
	ds_read_b64_tr_b16 v[142:143], v222 offset:31232
	s_waitcnt lgkmcnt(0)
; #define LAS __attribute__((address_space(3)))
; __device__ __forceinline__ unsigned pk2(float lo, float hi) { f32x2_t v = {lo, hi}; bf16x2_t b = __builtin_convertvector(v, bf16x2_t); return __builtin_bit_cast(unsigned, b); }
; __device__ __forceinline__ float ex2(float x) { return __builtin_amdgcn_exp2f(x); }
; template <int D, bool DIAG, int QT0>
; __device__ __forceinline__ void sm_pv_tile(f32x4 (&s)[4][2], const LAS unsigned char* Vs, int VP, f32x4 (&o)[D / 16][2], f32x4 (&ol)[2], int fr, int fq, int keyl0, int qla, int qlb) {
; #pragma unroll
;     for (int qt = QT0; qt < 2; ++qt) {
;         if (DIAG) {
;             const int ql = (qt == 0 ? qla : qlb) + fr - keyl0 - fq * 4;
; #pragma unroll
;             for (int a = 0; a < 4; ++a)
; #pragma unroll
;                 for (int jj = 0; jj < 4; ++jj) s[a][qt][jj] = (a * 16 + jj > ql) ? -1e30f : s[a][qt][jj];
;         }
; #pragma unroll
;         for (int a = 0; a < 4; ++a)
; #pragma unroll
;             for (int jj = 0; jj < 4; ++jj) s[a][qt][jj] = ex2(s[a][qt][jj]);
;     }
; #pragma unroll
;     for (int kst = 0; kst < 2; ++kst) {
;         bf16x8 pb[2];
; #pragma unroll
;         for (int qt = QT0; qt < 2; ++qt) { u32x4 pw; pw.x = pk2(s[2 * kst][qt][0], s[2 * kst][qt][1]); pw.y = pk2(s[2 * kst][qt][2], s[2 * kst][qt][3]);
;             pw.z = pk2(s[2 * kst + 1][qt][0], s[2 * kst + 1][qt][1]); pw.w = pk2(s[2 * kst + 1][qt][2], s[2 * kst + 1][qt][3]); pb[qt] = __builtin_bit_cast(bf16x8, pw); }
;         if (QT0 == 0) ol[0] = MFMA16(ONES8, pb[0], ol[0]);
;         ol[1] = MFMA16(ONES8, pb[1], ol[1]);
; #pragma unroll
;         for (int dt = 0; dt < D / 16; ++dt) { const s16x4 lo = tr4(Vs, VP, kst * 32 + fq * 4, dt * 16, fr), hi = tr4(Vs, VP, kst * 32 + 16 + fq * 4, dt * 16, fr);
;             const bf16x8 vf = __builtin_shufflevector(lo, hi, 0, 1, 2, 3, 4, 5, 6, 7);
;             if (QT0 == 0) o[dt][0] = MFMA16(vf, pb[0], o[dt][0]);
;             o[dt][1] = MFMA16(vf, pb[1], o[dt][1]); }
;     }
; __device__ __forceinline__ void mem_unit(const Args& a, int l, LAS unsigned char* lds, int b, int hm, int qb) {
;     ...
;     MEM_STORE(0);
;     BAR_LDS();
;     for (int kt = 0; kt < 4; ++kt) {
;         if (kt < 3) MEM_LOAD(kt + 1);
;         attn_tile<128, false, 0>(Ks + (kt & 1) * 35840, 272, Vs + (kt & 1) * 35840, 288, qf, o, ol, fr, fq, 0, 0, 0, -gm, -gm);
;         if (kt < 3) MEM_STORE((kt + 1) & 1);
	v_mfma_f32_16x16x32_bf16 v[84:87], v[140:143], v[132:135], v[84:87]
	v_mfma_f32_16x16x32_bf16 v[88:91], v[140:143], v[136:139], v[88:91]
	ds_read_b64_tr_b16 v[140:141], v222 offset:26656
	ds_read_b64_tr_b16 v[142:143], v222 offset:31264
	s_waitcnt lgkmcnt(0)
	v_mfma_f32_16x16x32_bf16 v[92:95], v[140:143], v[132:135], v[92:95]
	v_mfma_f32_16x16x32_bf16 v[96:99], v[140:143], v[136:139], v[96:99]
	ds_read_b64_tr_b16 v[140:141], v222 offset:26688
	ds_read_b64_tr_b16 v[142:143], v222 offset:31296
	s_waitcnt lgkmcnt(0)
	v_mfma_f32_16x16x32_bf16 v[76:79], v[140:143], v[132:135], v[76:79]
	v_mfma_f32_16x16x32_bf16 v[80:83], v[140:143], v[136:139], v[80:83]
	ds_read_b64_tr_b16 v[140:141], v218 offset:26624
	ds_read_b64_tr_b16 v[142:143], v218 offset:31232
	s_waitcnt lgkmcnt(0)
	v_mfma_f32_16x16x32_bf16 v[100:103], v[140:143], v[132:135], v[100:103]
	v_mfma_f32_16x16x32_bf16 v[104:107], v[140:143], v[136:139], v[104:107]
	ds_read_b64_tr_b16 v[140:141], v222 offset:26752
	ds_read_b64_tr_b16 v[142:143], v222 offset:31360
	s_waitcnt lgkmcnt(0)
	v_mfma_f32_16x16x32_bf16 v[64:67], v[140:143], v[132:135], v[64:67]
	v_mfma_f32_16x16x32_bf16 v[68:71], v[140:143], v[136:139], v[68:71]
	ds_read_b64_tr_b16 v[140:141], v222 offset:26784
	ds_read_b64_tr_b16 v[142:143], v222 offset:31392
	s_waitcnt lgkmcnt(0)
	v_mfma_f32_16x16x32_bf16 v[56:59], v[140:143], v[132:135], v[56:59]
	v_mfma_f32_16x16x32_bf16 v[60:63], v[140:143], v[136:139], v[60:63]
	ds_read_b64_tr_b16 v[140:141], v222 offset:26816
	ds_read_b64_tr_b16 v[142:143], v222 offset:31424
	s_waitcnt lgkmcnt(0)
	v_mfma_f32_16x16x32_bf16 v[48:51], v[140:143], v[132:135], v[48:51]
	v_mfma_f32_16x16x32_bf16 v[52:55], v[140:143], v[136:139], v[52:55]
	ds_read_b64_tr_b16 v[140:141], v213 offset:26624
	ds_read_b64_tr_b16 v[142:143], v213 offset:31232
	s_waitcnt lgkmcnt(0)
	v_mfma_f32_16x16x32_bf16 v[40:43], v[140:143], v[132:135], v[40:43]
	s_waitcnt vmcnt(3)
	v_lshlrev_b32_e32 v132, 16, v131
	v_and_b32_e32 v133, 0xffff0000, v131
	v_pk_mul_f32 v[134:135], v[132:133], v[132:133]
	v_mfma_f32_16x16x32_bf16 v[44:47], v[140:143], v[136:139], v[44:47]
	v_lshlrev_b32_e32 v142, 16, v128
	v_and_b32_e32 v143, 0xffff0000, v128
	v_lshlrev_b32_e32 v138, 16, v129
	v_and_b32_e32 v139, 0xffff0000, v129
	v_pk_mul_f32 v[128:129], v[142:143], v[142:143]
	v_pk_mul_f32 v[140:141], v[138:139], v[138:139]
	v_add_f32_e32 v128, v128, v129
	v_lshlrev_b32_e32 v136, 16, v130
	v_and_b32_e32 v137, 0xffff0000, v130
	v_add_f32_e32 v128, v140, v128
	v_pk_mul_f32 v[130:131], v[136:137], v[136:137]
	v_add_f32_e32 v128, v141, v128
	v_add_f32_e32 v128, v130, v128
	v_add_f32_e32 v128, v131, v128
	v_add_f32_e32 v128, v134, v128
	v_add_f32_e32 v128, v135, v128
	s_nop 1
	v_mov_b32_dpp v129, v128 quad_perm:[1,0,3,2] row_mask:0xf bank_mask:0xf
	s_waitcnt lgkmcnt(0)
	v_add_f32_e32 v128, v128, v129
	s_nop 1
	v_mov_b32_dpp v129, v128 quad_perm:[2,3,0,1] row_mask:0xf bank_mask:0xf
	s_waitcnt lgkmcnt(0)
	v_add_f32_e32 v128, v128, v129
	s_nop 1
	v_mov_b32_dpp v129, v128 row_half_mirror row_mask:0xf bank_mask:0xf
	s_waitcnt lgkmcnt(0)
	v_add_f32_e32 v128, v128, v129
	s_nop 1
	v_mov_b32_dpp v129, v128 row_mirror row_mask:0xf bank_mask:0xf
	s_waitcnt lgkmcnt(0)
	v_add_f32_e32 v128, v128, v129
	v_fmamk_f32 v128, v128, 0x3c000000, v186
	v_rsq_f32_e32 v134, v128
	s_nop 0
	v_pk_mul_f32 v[128:129], v[134:135], v[142:143] op_sel_hi:[0,1]
	v_pk_mul_f32 v[130:131], v[134:135], v[138:139] op_sel_hi:[0,1]
	v_pk_mul_f32 v[128:129], v[4:5], v[128:129]
	v_pk_mul_f32 v[130:131], v[6:7], v[130:131]
	v_cvt_pk_bf16_f32 v128, v128, v129
	v_cvt_pk_bf16_f32 v129, v130, v131
	v_pk_mul_f32 v[130:131], v[134:135], v[136:137] op_sel_hi:[0,1]
	v_pk_mul_f32 v[132:133], v[134:135], v[132:133] op_sel_hi:[0,1]
	v_pk_mul_f32 v[130:131], v[0:1], v[130:131]
	v_pk_mul_f32 v[132:133], v[2:3], v[132:133]
	v_cvt_pk_bf16_f32 v130, v130, v131
	v_cvt_pk_bf16_f32 v131, v132, v133
	v_add_u32_e32 v132, v181, v174
	s_waitcnt vmcnt(1)
	v_lshlrev_b32_e32 v134, 16, v120
	v_and_b32_e32 v135, 0xffff0000, v120
	ds_write_b128 v132, v[128:131]
	v_lshlrev_b32_e32 v130, 16, v121
	v_and_b32_e32 v131, 0xffff0000, v121
	v_pk_mul_f32 v[120:121], v[134:135], v[134:135]
	v_add_u32_e32 v128, v181, v175
	v_pk_mul_f32 v[132:133], v[130:131], v[130:131]
	v_add_f32_e32 v120, v120, v121
	ds_write_b128 v128, v[124:127] offset:17408
	v_lshlrev_b32_e32 v128, 16, v122
	v_and_b32_e32 v129, 0xffff0000, v122
	v_add_f32_e32 v120, v132, v120
	v_lshlrev_b32_e32 v124, 16, v123
	v_and_b32_e32 v125, 0xffff0000, v123
	v_pk_mul_f32 v[122:123], v[128:129], v[128:129]
	v_add_f32_e32 v120, v133, v120
	v_add_f32_e32 v120, v122, v120
	v_pk_mul_f32 v[126:127], v[124:125], v[124:125]
	v_add_f32_e32 v120, v123, v120
	v_add_f32_e32 v120, v126, v120
	v_add_f32_e32 v120, v127, v120
	s_nop 1
	v_mov_b32_dpp v121, v120 quad_perm:[1,0,3,2] row_mask:0xf bank_mask:0xf
	s_waitcnt lgkmcnt(0)
	v_add_f32_e32 v120, v120, v121
	s_nop 1
	v_mov_b32_dpp v121, v120 quad_perm:[2,3,0,1] row_mask:0xf bank_mask:0xf
	s_waitcnt lgkmcnt(0)
	v_add_f32_e32 v120, v120, v121
	s_nop 1
	v_mov_b32_dpp v121, v120 row_half_mirror row_mask:0xf bank_mask:0xf
	s_waitcnt lgkmcnt(0)
	v_add_f32_e32 v120, v120, v121
	s_nop 1
	v_mov_b32_dpp v121, v120 row_mirror row_mask:0xf bank_mask:0xf
	s_waitcnt lgkmcnt(0)
	v_add_f32_e32 v120, v120, v121
	v_fmamk_f32 v120, v120, 0x3c000000, v186
	v_rsq_f32_e32 v126, v120
	s_nop 0
	v_pk_mul_f32 v[120:121], v[126:127], v[134:135] op_sel_hi:[0,1]
	v_pk_mul_f32 v[122:123], v[126:127], v[130:131] op_sel_hi:[0,1]
	v_pk_mul_f32 v[120:121], v[4:5], v[120:121]
	v_pk_mul_f32 v[122:123], v[6:7], v[122:123]
	v_cvt_pk_bf16_f32 v120, v120, v121
	v_cvt_pk_bf16_f32 v121, v122, v123
	v_pk_mul_f32 v[122:123], v[126:127], v[128:129] op_sel_hi:[0,1]
	v_pk_mul_f32 v[124:125], v[126:127], v[124:125] op_sel_hi:[0,1]
	v_pk_mul_f32 v[122:123], v[0:1], v[122:123]
	v_pk_mul_f32 v[124:125], v[2:3], v[124:125]
	v_cvt_pk_bf16_f32 v122, v122, v123
	v_cvt_pk_bf16_f32 v123, v124, v125
	v_add_u32_e32 v124, v181, v177
	ds_write_b128 v124, v[120:123]
	v_add_u32_e32 v120, v181, v180
	s_waitcnt vmcnt(0)
	ds_write_b128 v120, v[116:119] offset:17408
	s_waitcnt lgkmcnt(0)
	s_barrier
; #define LAS __attribute__((address_space(3)))
; __device__ __forceinline__ float frcp(float x) { return __builtin_amdgcn_rcpf(x); }
; #define MFMA16(a, b, c) __builtin_amdgcn_mfma_f32_16x16x32_bf16((a), (b), (c), 0, 0, 0)
; #define BAR_LDS() do { asm volatile("s_waitcnt lgkmcnt(0)" ::: "memory"); __builtin_amdgcn_s_barrier(); asm volatile("" ::: "memory"); } while (0)
; #define MEM_LOAD(kt) do { _Pragma("unroll") for (int ii = 0; ii < 2; ++ii) { const int cid = tid + 512 * ii; \
;         ukr[ii] = *(const u32x4*)(kvm + (size_t)((kt) * 64 + (cid >> 4)) * 1024 + hm * 128 + (cid & 15) * 8); \
;         uvr[ii] = *(const u32x4*)(kvm + (size_t)((kt) * 64 + (cid >> 4)) * 1024 + 512 + hm * 128 + (cid & 15) * 8); } } while (0)
; template <int D, int QT0>
; __device__ __forceinline__ void qk_tile(const LAS unsigned char* Ks, int KP, const bf16x8 (&qf)[2][D / 32], f32x4 (&s)[4][2], int fr, int fq, float b0, float b1) {
; #pragma unroll
;     for (int a = 0; a < 4; ++a) { s[a][0] = (f32x4){b0, b0, b0, b0}; s[a][1] = (f32x4){b1, b1, b1, b1}; }
; #pragma unroll
;     for (int a = 0; a < 4; ++a)
; #pragma unroll
;         for (int ks = 0; ks < D / 32; ++ks) { const bf16x8 kfr = *(const LAS bf16x8*)(Ks + (a * 16 + fr) * KP + (ks * 32 + fq * 8) * 2);
;             if (QT0 == 0) s[a][0] = MFMA16(kfr, qf[0][ks], s[a][0]);
;             s[a][1] = MFMA16(kfr, qf[1][ks], s[a][1]); }
; }
; __device__ __forceinline__ void mem_unit(const Args& a, int l, LAS unsigned char* lds, int b, int hm, int qb) {
;     ...
;     for (int kt = 0; kt < 4; ++kt) {
;         if (kt < 3) MEM_LOAD(kt + 1);
;         attn_tile<128, false, 0>(Ks + (kt & 1) * 35840, 272, Vs + (kt & 1) * 35840, 288, qf, o, ol, fr, fq, 0, 0, 0, -gm, -gm);
;         if (kt < 3) MEM_STORE((kt + 1) & 1);
;         BAR_LDS();
;     }
;     ...
; #pragma unroll
;     for (int qt = 0; qt < 2; ++qt) {
;         const float inv = frcp(ol[qt][0]);
;         const size_t row = rowbase + q0 + qt * 16 + fr;
; #pragma unroll
;         for (int dt = 0; dt < 8; ++dt) { const int d0 = dt * 16 + fq * 4;
;             const u32x2 z = *(const u32x2*)(proj + row * NCOL + CZ + 1024 + hm * 128 + d0);
	s_cbranch_scc1 .LBB0_520
	ds_read_b128 v[0:3], v176 offset:35840
	ds_read_b128 v[118:121], v176 offset:35904
	v_add_u32_e32 v141, v172, v170
	v_add_u32_e32 v116, 0x4400, v172
	s_lshl_b32 s6, s8, 1
	v_lshlrev_b32_e32 v144, 1, v144
	s_mov_b64 s[4:5], 0x1400
	v_lshl_add_u64 v[164:165], v[162:163], 0, s[6:7]
	v_lshl_add_u64 v[166:167], v[158:159], 0, s[6:7]
	v_lshl_add_u64 v[164:165], v[164:165], 0, v[144:145]
	v_lshl_add_u64 v[166:167], v[166:167], 0, v[144:145]
	v_lshl_add_u64 v[164:165], v[164:165], 0, s[4:5]
	v_lshl_add_u64 v[166:167], v[166:167], 0, s[4:5]
	global_load_dwordx2 v[200:201], v[164:165], off
	global_load_dwordx2 v[202:203], v[164:165], off offset:32
	global_load_dwordx2 v[204:205], v[164:165], off offset:64
	global_load_dwordx2 v[206:207], v[164:165], off offset:96
	global_load_dwordx2 v[208:209], v[164:165], off offset:128
	global_load_dwordx2 v[210:211], v[164:165], off offset:160
	global_load_dwordx2 v[212:213], v[164:165], off offset:192
	global_load_dwordx2 v[214:215], v[164:165], off offset:224
	global_load_dwordx2 v[216:217], v[166:167], off
	global_load_dwordx2 v[218:219], v[166:167], off offset:32
	global_load_dwordx2 v[220:221], v[166:167], off offset:64
	global_load_dwordx2 v[222:223], v[166:167], off offset:96
	global_load_dwordx2 v[224:225], v[166:167], off offset:128
	global_load_dwordx2 v[226:227], v[166:167], off offset:160
	global_load_dwordx2 v[228:229], v[166:167], off offset:192
	global_load_dwordx2 v[230:231], v[166:167], off offset:224
	v_lshlrev_b32_e32 v142, 1, v144
	v_mov_b32_e32 v143, 0
	s_add_i32 s14, s14, s3
	s_cmpk_gt_i32 s14, 0xff
	s_waitcnt lgkmcnt(1)
	v_mfma_f32_16x16x32_bf16 v[4:7], v[0:3], v[16:19], v[72:75]
	ds_read_b128 v[126:129], v176 offset:40256
	ds_read_b128 v[134:137], v176 offset:44608
	v_mfma_f32_16x16x32_bf16 v[0:3], v[0:3], v[24:27], v[72:75]
	s_waitcnt lgkmcnt(2)
	v_mfma_f32_16x16x32_bf16 v[4:7], v[118:121], v[20:23], v[4:7]
	v_mfma_f32_16x16x32_bf16 v[0:3], v[118:121], v[28:31], v[0:3]
	ds_read_b128 v[118:121], v176 offset:35968
	s_waitcnt lgkmcnt(0)
	v_mfma_f32_16x16x32_bf16 v[4:7], v[118:121], v[12:15], v[4:7]
	v_mfma_f32_16x16x32_bf16 v[0:3], v[118:121], v[36:39], v[0:3]
	ds_read_b128 v[118:121], v176 offset:36032
	s_waitcnt lgkmcnt(0)
	v_mfma_f32_16x16x32_bf16 v[4:7], v[118:121], v[8:11], v[4:7]
	s_nop 7
	v_exp_f32_e32 v4, v4
	v_mfma_f32_16x16x32_bf16 v[0:3], v[118:121], v[32:35], v[0:3]
	ds_read_b128 v[118:121], v176 offset:40192
	v_exp_f32_e32 v5, v5
	v_exp_f32_e32 v6, v6
	s_waitcnt lgkmcnt(0)
	v_mfma_f32_16x16x32_bf16 v[122:125], v[118:121], v[16:19], v[72:75]
	v_exp_f32_e32 v7, v7
	s_nop 1
	v_exp_f32_e32 v0, v0
	v_exp_f32_e32 v1, v1
	v_mfma_f32_16x16x32_bf16 v[118:121], v[118:121], v[24:27], v[72:75]
	v_exp_f32_e32 v2, v2
	v_exp_f32_e32 v3, v3
	v_mfma_f32_16x16x32_bf16 v[122:125], v[126:129], v[20:23], v[122:125]
	v_mfma_f32_16x16x32_bf16 v[118:121], v[126:129], v[28:31], v[118:121]
	ds_read_b128 v[126:129], v176 offset:40320
	s_waitcnt lgkmcnt(0)
	v_mfma_f32_16x16x32_bf16 v[122:125], v[126:129], v[12:15], v[122:125]
	v_mfma_f32_16x16x32_bf16 v[118:121], v[126:129], v[36:39], v[118:121]
	ds_read_b128 v[126:129], v176 offset:40384
	s_waitcnt lgkmcnt(0)
	v_mfma_f32_16x16x32_bf16 v[122:125], v[126:129], v[8:11], v[122:125]
	v_mfma_f32_16x16x32_bf16 v[118:121], v[126:129], v[32:35], v[118:121]
	ds_read_b128 v[126:129], v176 offset:44544
	s_waitcnt lgkmcnt(0)
	v_mfma_f32_16x16x32_bf16 v[130:133], v[126:129], v[16:19], v[72:75]
	v_mfma_f32_16x16x32_bf16 v[126:129], v[126:129], v[24:27], v[72:75]
	v_mfma_f32_16x16x32_bf16 v[130:133], v[134:137], v[20:23], v[130:133]
	v_mfma_f32_16x16x32_bf16 v[126:129], v[134:137], v[28:31], v[126:129]
	ds_read_b128 v[134:137], v176 offset:44672
	s_waitcnt lgkmcnt(0)
	v_mfma_f32_16x16x32_bf16 v[130:133], v[134:137], v[12:15], v[130:133]
	v_mfma_f32_16x16x32_bf16 v[126:129], v[134:137], v[36:39], v[126:129]
	ds_read_b128 v[134:137], v176 offset:44736
	s_waitcnt lgkmcnt(0)
	v_mfma_f32_16x16x32_bf16 v[130:133], v[134:137], v[8:11], v[130:133]
	v_mfma_f32_16x16x32_bf16 v[126:129], v[134:137], v[32:35], v[126:129]
	ds_read_b128 v[134:137], v176 offset:48896
	s_waitcnt lgkmcnt(0)
	v_mfma_f32_16x16x32_bf16 v[16:19], v[134:137], v[16:19], v[72:75]
	s_nop 4
	v_exp_f32_e32 v117, v126
	v_mfma_f32_16x16x32_bf16 v[24:27], v[134:137], v[24:27], v[72:75]
	v_exp_f32_e32 v134, v127
	v_exp_f32_e32 v135, v128
	v_exp_f32_e32 v136, v129
	ds_read_b128 v[72:75], v176 offset:48960
	s_waitcnt lgkmcnt(0)
	v_mfma_f32_16x16x32_bf16 v[16:19], v[72:75], v[20:23], v[16:19]
	v_mfma_f32_16x16x32_bf16 v[20:23], v[72:75], v[28:31], v[24:27]
	s_nop 2
	ds_read_b128 v[24:27], v176 offset:49024
	s_waitcnt lgkmcnt(0)
	v_mfma_f32_16x16x32_bf16 v[12:15], v[24:27], v[12:15], v[16:19]
	v_mfma_f32_16x16x32_bf16 v[16:19], v[24:27], v[36:39], v[20:23]
	v_exp_f32_e32 v38, v132
	v_exp_f32_e32 v39, v133
	s_nop 0
	ds_read_b128 v[20:23], v176 offset:49088
	s_waitcnt lgkmcnt(0)
	v_mfma_f32_16x16x32_bf16 v[8:11], v[20:23], v[8:11], v[12:15]
	ds_read_b64_tr_b16 v[26:27], v141 offset:57856
	ds_read_b64_tr_b16 v[24:25], v141 offset:53248
	ds_read_b64_tr_b16 v[28:29], v141 offset:53280
	ds_read_b64_tr_b16 v[30:31], v141 offset:57888
	s_nop 3
	v_exp_f32_e32 v72, v8
	v_mfma_f32_16x16x32_bf16 v[12:15], v[20:23], v[32:35], v[16:19]
	v_exp_f32_e32 v73, v9
	v_exp_f32_e32 v74, v10
	v_exp_f32_e32 v75, v11
	v_exp_f32_e32 v16, v122
	v_exp_f32_e32 v17, v123
	v_exp_f32_e32 v18, v124
	v_exp_f32_e32 v19, v125
	v_exp_f32_e32 v8, v118
	v_exp_f32_e32 v9, v119
	v_exp_f32_e32 v10, v120
	v_exp_f32_e32 v11, v121
	v_exp_f32_e32 v137, v12
	v_exp_f32_e32 v138, v13
	v_exp_f32_e32 v139, v14
	v_exp_f32_e32 v140, v15
	v_cvt_pk_bf16_f32 v12, v4, v5
	v_cvt_pk_bf16_f32 v13, v6, v7
	v_cvt_pk_bf16_f32 v14, v16, v17
	v_cvt_pk_bf16_f32 v15, v18, v19
	v_cvt_pk_bf16_f32 v16, v0, v1
	v_cvt_pk_bf16_f32 v17, v2, v3
	v_cvt_pk_bf16_f32 v18, v8, v9
	v_cvt_pk_bf16_f32 v19, v10, v11
	s_waitcnt lgkmcnt(2)
; #define LAS __attribute__((address_space(3)))
; __device__ __forceinline__ unsigned pk2(float lo, float hi) { f32x2_t v = {lo, hi}; bf16x2_t b = __builtin_convertvector(v, bf16x2_t); return __builtin_bit_cast(unsigned, b); }
; __device__ __forceinline__ float ex2(float x) { return __builtin_amdgcn_exp2f(x); }
; __device__ __forceinline__ float frcp(float x) { return __builtin_amdgcn_rcpf(x); }
; template <int D, bool DIAG, int QT0>
; __device__ __forceinline__ void sm_pv_tile(f32x4 (&s)[4][2], const LAS unsigned char* Vs, int VP, f32x4 (&o)[D / 16][2], f32x4 (&ol)[2], int fr, int fq, int keyl0, int qla, int qlb) {
; #pragma unroll
;     for (int qt = QT0; qt < 2; ++qt) {
;         if (DIAG) {
;             const int ql = (qt == 0 ? qla : qlb) + fr - keyl0 - fq * 4;
; #pragma unroll
;             for (int a = 0; a < 4; ++a)
; #pragma unroll
;                 for (int jj = 0; jj < 4; ++jj) s[a][qt][jj] = (a * 16 + jj > ql) ? -1e30f : s[a][qt][jj];
;         }
; #pragma unroll
;         for (int a = 0; a < 4; ++a)
; #pragma unroll
;             for (int jj = 0; jj < 4; ++jj) s[a][qt][jj] = ex2(s[a][qt][jj]);
;     }
; #pragma unroll
;     for (int kst = 0; kst < 2; ++kst) {
;         bf16x8 pb[2];
; #pragma unroll
;         for (int qt = QT0; qt < 2; ++qt) { u32x4 pw; pw.x = pk2(s[2 * kst][qt][0], s[2 * kst][qt][1]); pw.y = pk2(s[2 * kst][qt][2], s[2 * kst][qt][3]);
;             pw.z = pk2(s[2 * kst + 1][qt][0], s[2 * kst + 1][qt][1]); pw.w = pk2(s[2 * kst + 1][qt][2], s[2 * kst + 1][qt][3]); pb[qt] = __builtin_bit_cast(bf16x8, pw); }
;         if (QT0 == 0) ol[0] = MFMA16(ONES8, pb[0], ol[0]);
;         ol[1] = MFMA16(ONES8, pb[1], ol[1]);
; #pragma unroll
;         for (int dt = 0; dt < D / 16; ++dt) { const s16x4 lo = tr4(Vs, VP, kst * 32 + fq * 4, dt * 16, fr), hi = tr4(Vs, VP, kst * 32 + 16 + fq * 4, dt * 16, fr);
;             const bf16x8 vf = __builtin_shufflevector(lo, hi, 0, 1, 2, 3, 4, 5, 6, 7);
;             if (QT0 == 0) o[dt][0] = MFMA16(vf, pb[0], o[dt][0]);
;             o[dt][1] = MFMA16(vf, pb[1], o[dt][1]); }
;     }
; __device__ __forceinline__ void mem_unit(const Args& a, int l, LAS unsigned char* lds, int b, int hm, int qb) {
;     ...
; #pragma unroll
;     for (int qt = 0; qt < 2; ++qt) {
;         const float inv = frcp(ol[qt][0]);
;         const size_t row = rowbase + q0 + qt * 16 + fr;
; #pragma unroll
	v_mfma_f32_16x16x32_bf16 v[20:23], v[24:27], v[12:15], v[84:87]
	v_mov_b64_e32 v[0:1], s[68:69]
	v_mov_b64_e32 v[2:3], s[70:71]
	v_exp_f32_e32 v32, v130
	v_mfma_f32_16x16x32_bf16 v[24:27], v[24:27], v[16:19], v[88:91]
	v_exp_f32_e32 v33, v131
	v_cvt_pk_bf16_f32 v72, v72, v73
	v_cvt_pk_bf16_f32 v73, v74, v75
	s_waitcnt lgkmcnt(0)
	v_mfma_f32_16x16x32_bf16 v[84:87], v[28:31], v[12:15], v[92:95]
	v_cvt_pk_bf16_f32 v74, v117, v134
	v_cvt_pk_bf16_f32 v75, v135, v136
	v_mfma_f32_16x16x32_bf16 v[88:91], v[28:31], v[16:19], v[96:99]
	ds_read_b64_tr_b16 v[28:29], v141 offset:53312
	ds_read_b64_tr_b16 v[30:31], v141 offset:57920
	s_waitcnt lgkmcnt(0)
	v_mfma_f32_16x16x32_bf16 v[96:99], v[28:31], v[16:19], v[80:83]
	s_nop 2
	v_add_u32_e32 v82, v172, v169
	v_add_u32_e32 v83, v172, v168
	v_mfma_f32_16x16x32_bf16 v[92:95], v[28:31], v[12:15], v[76:79]
	ds_read_b64_tr_b16 v[28:29], v82 offset:53248
	ds_read_b64_tr_b16 v[30:31], v82 offset:57856
	s_nop 0
	v_cvt_pk_bf16_f32 v76, v137, v138
	s_waitcnt lgkmcnt(0)
	v_mfma_f32_16x16x32_bf16 v[100:103], v[28:31], v[12:15], v[100:103]
	v_cvt_pk_bf16_f32 v77, v139, v140
	v_mfma_f32_16x16x32_bf16 v[104:107], v[28:31], v[16:19], v[104:107]
	ds_read_b64_tr_b16 v[28:29], v141 offset:53376
	ds_read_b64_tr_b16 v[30:31], v141 offset:57984
	v_mfma_f32_16x16x32_bf16 v[4:7], v[0:3], v[12:15], v[108:111]
	v_mfma_f32_16x16x32_bf16 v[8:11], v[0:3], v[16:19], v[112:115]
	s_waitcnt lgkmcnt(0)
	v_mfma_f32_16x16x32_bf16 v[108:111], v[28:31], v[12:15], v[64:67]
	v_mfma_f32_16x16x32_bf16 v[112:115], v[28:31], v[16:19], v[68:71]
	ds_read_b64_tr_b16 v[28:29], v141 offset:53408
	ds_read_b64_tr_b16 v[30:31], v141 offset:58016
	s_nop 0
	v_cvt_pk_bf16_f32 v70, v32, v33
	s_waitcnt lgkmcnt(0)
	v_mfma_f32_16x16x32_bf16 v[118:121], v[28:31], v[12:15], v[56:59]
	v_cvt_pk_bf16_f32 v71, v38, v39
	v_mfma_f32_16x16x32_bf16 v[122:125], v[28:31], v[16:19], v[60:63]
	ds_read_b64_tr_b16 v[28:29], v141 offset:53440
	ds_read_b64_tr_b16 v[30:31], v141 offset:58048
	s_waitcnt lgkmcnt(0)
	v_mfma_f32_16x16x32_bf16 v[126:129], v[28:31], v[12:15], v[48:51]
	v_mfma_f32_16x16x32_bf16 v[130:133], v[28:31], v[16:19], v[52:55]
	ds_read_b64_tr_b16 v[28:29], v83 offset:53248
	ds_read_b64_tr_b16 v[30:31], v83 offset:57856
	s_waitcnt lgkmcnt(0)
	v_mfma_f32_16x16x32_bf16 v[34:37], v[28:31], v[12:15], v[40:43]
	v_mfma_f32_16x16x32_bf16 v[66:69], v[28:31], v[16:19], v[44:47]
	v_mfma_f32_16x16x32_bf16 v[62:65], v[0:3], v[70:73], v[4:7]
	v_mfma_f32_16x16x32_bf16 v[28:31], v[0:3], v[74:77], v[8:11]
	ds_read_b64_tr_b16 v[0:1], v141 offset:62464
	s_nop 0
	v_add_u32_e32 v6, v116, v170
	ds_read_b64_tr_b16 v[2:3], v6 offset:49664
	ds_read_b64_tr_b16 v[4:5], v6 offset:49696
	s_waitcnt lgkmcnt(1)
	v_mfma_f32_16x16x32_bf16 v[78:81], v[0:3], v[70:73], v[20:23]
	v_lshl_add_u64 v[64:65], v[162:163], 0, s[6:7]
	v_lshl_add_u64 v[64:65], v[64:65], 0, v[144:145]
	v_rcp_f32_e32 v62, v62
	v_mfma_f32_16x16x32_bf16 v[30:33], v[0:3], v[74:77], v[24:27]
	ds_read_b64_tr_b16 v[2:3], v141 offset:62496
	s_waitcnt lgkmcnt(0)
	v_mfma_f32_16x16x32_bf16 v[58:61], v[2:5], v[70:73], v[84:87]
	s_nop 7
	v_pk_mul_f32 v[58:59], v[62:63], v[58:59] op_sel_hi:[0,1]
	v_mfma_f32_16x16x32_bf16 v[24:27], v[2:5], v[74:77], v[88:91]
	ds_read_b64_tr_b16 v[0:1], v141 offset:62528
	ds_read_b64_tr_b16 v[2:3], v6 offset:49728
	v_pk_mul_f32 v[60:61], v[62:63], v[60:61] op_sel_hi:[0,1]
	s_waitcnt lgkmcnt(0)
	v_mfma_f32_16x16x32_bf16 v[54:57], v[0:3], v[70:73], v[92:95]
	v_mfma_f32_16x16x32_bf16 v[20:23], v[0:3], v[74:77], v[96:99]
	v_add_u32_e32 v2, v116, v169
	ds_read_b64_tr_b16 v[0:1], v82 offset:62464
	ds_read_b64_tr_b16 v[2:3], v2 offset:49664
	s_waitcnt lgkmcnt(0)
	v_mfma_f32_16x16x32_bf16 v[50:53], v[0:3], v[70:73], v[100:103]
	s_nop 1
	v_mul_f32_e64 v54, v62, v54
	v_mul_f32_e64 v55, v62, v55
	v_pk_mul_f32 v[56:57], v[62:63], v[56:57] op_sel_hi:[0,1]
	s_nop 2
	v_pk_mul_f32 v[50:51], v[62:63], v[50:51] op_sel_hi:[0,1]
	v_mfma_f32_16x16x32_bf16 v[16:19], v[0:3], v[74:77], v[104:107]
	ds_read_b64_tr_b16 v[0:1], v141 offset:62592
	ds_read_b64_tr_b16 v[2:3], v6 offset:49792
	v_pk_mul_f32 v[52:53], v[62:63], v[52:53] op_sel_hi:[0,1]
	s_waitcnt lgkmcnt(0)
	v_mfma_f32_16x16x32_bf16 v[46:49], v[0:3], v[70:73], v[108:111]
	v_mfma_f32_16x16x32_bf16 v[12:15], v[0:3], v[74:77], v[112:115]
	ds_read_b64_tr_b16 v[0:1], v141 offset:62624
	ds_read_b64_tr_b16 v[2:3], v6 offset:49824
	s_nop 4
	v_pk_mul_f32 v[46:47], v[62:63], v[46:47] op_sel_hi:[0,1]
	v_pk_mul_f32 v[48:49], v[62:63], v[48:49] op_sel_hi:[0,1]
	s_waitcnt lgkmcnt(0)
	v_mfma_f32_16x16x32_bf16 v[42:45], v[0:3], v[70:73], v[118:121]
	v_mfma_f32_16x16x32_bf16 v[8:11], v[0:3], v[74:77], v[122:125]
	ds_read_b64_tr_b16 v[0:1], v141 offset:62656
	ds_read_b64_tr_b16 v[2:3], v6 offset:49856
	s_nop 4
	v_pk_mul_f32 v[42:43], v[62:63], v[42:43] op_sel_hi:[0,1]
	v_pk_mul_f32 v[44:45], v[62:63], v[44:45] op_sel_hi:[0,1]
	s_waitcnt lgkmcnt(0)
	v_mfma_f32_16x16x32_bf16 v[38:41], v[0:3], v[70:73], v[126:129]
	v_mfma_f32_16x16x32_bf16 v[4:7], v[0:3], v[74:77], v[130:133]
	v_add_u32_e32 v2, v116, v168
	ds_read_b64_tr_b16 v[0:1], v83 offset:62464
	ds_read_b64_tr_b16 v[2:3], v2 offset:49664
	s_waitcnt lgkmcnt(0)
	v_mfma_f32_16x16x32_bf16 v[34:37], v[0:3], v[70:73], v[34:37]
	s_waitcnt lgkmcnt(0)
	s_barrier
; __device__ __forceinline__ unsigned pk2(float lo, float hi) { f32x2_t v = {lo, hi}; bf16x2_t b = __builtin_convertvector(v, bf16x2_t); return __builtin_bit_cast(unsigned, b); }
; __device__ __forceinline__ float bflo(unsigned u) { return __uint_as_float(u << 16); }
; __device__ __forceinline__ float bfhi(unsigned u) { return __uint_as_float(u & 0xffff0000u); }
; __device__ __forceinline__ float frcp(float x) { return __builtin_amdgcn_rcpf(x); }
; __device__ __forceinline__ float silu(float x) { return x * frcp(1.f + fexp(-x)); }
; __device__ __forceinline__ void mem_unit(const Args& a, int l, LAS unsigned char* lds, int b, int hm, int qb) {
;     ...
; #pragma unroll
;     for (int qt = 0; qt < 2; ++qt) {
;         const float inv = frcp(ol[qt][0]);
;         const size_t row = rowbase + q0 + qt * 16 + fr;
; #pragma unroll
;         for (int dt = 0; dt < 8; ++dt) { const int d0 = dt * 16 + fq * 4;
;             const u32x2 z = *(const u32x2*)(proj + row * NCOL + CZ + 1024 + hm * 128 + d0);
;             u32x2 y; y.x = pk2(o[dt][qt][0] * inv * silu(bflo(z.x)), o[dt][qt][1] * inv * silu(bfhi(z.x))); y.y = pk2(o[dt][qt][2] * inv * silu(bflo(z.y)), o[dt][qt][3] * inv * silu(bfhi(z.y)));
;             *(u32x2*)(proj + row * NCOL + CQM + hm * 128 + d0) = y; }
	v_mfma_f32_16x16x32_bf16 v[0:3], v[0:3], v[74:77], v[66:69]
	v_mul_f32_e64 v72, v62, v78
	v_mul_f32_e64 v73, v62, v79
	v_pk_mul_f32 v[38:39], v[62:63], v[38:39] op_sel_hi:[0,1]
	v_pk_mul_f32 v[40:41], v[62:63], v[40:41] op_sel_hi:[0,1]
	v_lshl_add_u64 v[66:67], v[64:65], 0, s[4:5]
	v_add_co_u32_e32 v64, vcc, s26, v64
	v_pk_mul_f32 v[34:35], v[62:63], v[34:35] op_sel_hi:[0,1]
	s_nop 0
	v_addc_co_u32_e32 v65, vcc, 0, v65, vcc
	s_waitcnt vmcnt(0)
	v_mov_b64_e32 v[64:65], v[200:201]
	v_pk_mul_f32 v[36:37], v[62:63], v[36:37] op_sel_hi:[0,1]
	s_waitcnt vmcnt(0)
	v_lshlrev_b32_e32 v68, 16, v64
	v_mul_f32_e32 v29, 0xbfb8aa3b, v68
	v_exp_f32_e32 v29, v29
	v_and_b32_e32 v69, 0xffff0000, v64
	v_lshlrev_b32_e32 v64, 16, v65
	v_and_b32_e32 v65, 0xffff0000, v65
	v_add_f32_e32 v29, 1.0, v29
	v_rcp_f32_e32 v70, v29
	v_mul_f32_e32 v29, 0xbfb8aa3b, v69
	v_exp_f32_e32 v29, v29
	s_nop 0
	v_add_f32_e32 v29, 1.0, v29
	v_rcp_f32_e32 v71, v29
	v_mul_f32_e32 v29, 0xbfb8aa3b, v64
	v_exp_f32_e32 v29, v29
	v_pk_mul_f32 v[68:69], v[70:71], v[68:69]
	s_nop 0
	v_pk_mul_f32 v[68:69], v[72:73], v[68:69]
	v_add_f32_e32 v29, 1.0, v29
	v_rcp_f32_e32 v70, v29
	v_mul_f32_e32 v29, 0xbfb8aa3b, v65
	v_exp_f32_e32 v29, v29
	v_pk_mul_f32 v[72:73], v[62:63], v[80:81] op_sel_hi:[0,1]
	v_cvt_pk_bf16_f32 v68, v68, v69
	v_add_f32_e32 v29, 1.0, v29
	v_rcp_f32_e32 v71, v29
	s_nop 0
	v_pk_mul_f32 v[64:65], v[70:71], v[64:65]
	s_nop 0
	v_pk_mul_f32 v[64:65], v[72:73], v[64:65]
	s_nop 0
	v_cvt_pk_bf16_f32 v69, v64, v65
	v_lshl_add_u64 v[64:65], v[160:161], 0, v[142:143]
	v_mov_b64_e32 v[232:233], v[68:69]
	v_mov_b64_e32 v[68:69], v[202:203]
	v_lshlrev_b32_e32 v70, 16, v68
	v_mul_f32_e32 v29, 0xbfb8aa3b, v70
	v_exp_f32_e32 v29, v29
	v_and_b32_e32 v71, 0xffff0000, v68
	v_lshlrev_b32_e32 v68, 16, v69
	v_and_b32_e32 v69, 0xffff0000, v69
	v_add_f32_e32 v29, 1.0, v29
	v_rcp_f32_e32 v72, v29
	v_mul_f32_e32 v29, 0xbfb8aa3b, v71
	v_exp_f32_e32 v29, v29
	s_nop 0
	v_add_f32_e32 v29, 1.0, v29
	v_rcp_f32_e32 v73, v29
	v_mul_f32_e32 v29, 0xbfb8aa3b, v68
	v_exp_f32_e32 v29, v29
	v_pk_mul_f32 v[70:71], v[72:73], v[70:71]
	s_nop 0
	v_pk_mul_f32 v[58:59], v[58:59], v[70:71]
	v_add_f32_e32 v29, 1.0, v29
	v_rcp_f32_e32 v70, v29
	v_mul_f32_e32 v29, 0xbfb8aa3b, v69
	v_exp_f32_e32 v29, v29
	v_cvt_pk_bf16_f32 v58, v58, v59
	v_add_f32_e32 v29, 1.0, v29
	v_rcp_f32_e32 v71, v29
	s_nop 0
	v_pk_mul_f32 v[68:69], v[70:71], v[68:69]
	s_nop 0
	v_pk_mul_f32 v[60:61], v[60:61], v[68:69]
	s_nop 0
	v_cvt_pk_bf16_f32 v59, v60, v61
	v_mov_b64_e32 v[234:235], v[58:59]
	global_store_dwordx4 v[64:65], v[232:235], off offset:2048
	v_mov_b64_e32 v[58:59], v[204:205]
	v_lshlrev_b32_e32 v60, 16, v58
	v_mul_f32_e32 v29, 0xbfb8aa3b, v60
	v_exp_f32_e32 v29, v29
	v_and_b32_e32 v61, 0xffff0000, v58
	v_lshlrev_b32_e32 v58, 16, v59
	v_and_b32_e32 v59, 0xffff0000, v59
	v_add_f32_e32 v29, 1.0, v29
	v_rcp_f32_e32 v68, v29
	v_mul_f32_e32 v29, 0xbfb8aa3b, v61
	v_exp_f32_e32 v29, v29
	s_nop 0
	v_add_f32_e32 v29, 1.0, v29
	v_rcp_f32_e32 v69, v29
	v_mul_f32_e32 v29, 0xbfb8aa3b, v58
	v_exp_f32_e32 v29, v29
	v_pk_mul_f32 v[60:61], v[68:69], v[60:61]
	s_nop 0
	v_pk_mul_f32 v[54:55], v[54:55], v[60:61]
	v_add_f32_e32 v29, 1.0, v29
	v_rcp_f32_e32 v60, v29
	v_mul_f32_e32 v29, 0xbfb8aa3b, v59
	v_exp_f32_e32 v29, v29
	v_cvt_pk_bf16_f32 v54, v54, v55
	v_add_f32_e32 v29, 1.0, v29
	v_rcp_f32_e32 v61, v29
	s_nop 0
	v_pk_mul_f32 v[58:59], v[60:61], v[58:59]
	s_nop 0
	v_pk_mul_f32 v[56:57], v[56:57], v[58:59]
	s_nop 0
	v_cvt_pk_bf16_f32 v55, v56, v57
	v_mov_b64_e32 v[236:237], v[54:55]
	v_mov_b64_e32 v[54:55], v[206:207]
	v_lshlrev_b32_e32 v56, 16, v54
	v_mul_f32_e32 v29, 0xbfb8aa3b, v56
	v_exp_f32_e32 v29, v29
	v_and_b32_e32 v57, 0xffff0000, v54
	v_lshlrev_b32_e32 v54, 16, v55
	v_and_b32_e32 v55, 0xffff0000, v55
	v_add_f32_e32 v29, 1.0, v29
	v_rcp_f32_e32 v58, v29
	v_mul_f32_e32 v29, 0xbfb8aa3b, v57
	v_exp_f32_e32 v29, v29
	s_nop 0
	v_add_f32_e32 v29, 1.0, v29
	v_rcp_f32_e32 v59, v29
	v_mul_f32_e32 v29, 0xbfb8aa3b, v54
	v_exp_f32_e32 v29, v29
	v_pk_mul_f32 v[56:57], v[58:59], v[56:57]
	s_nop 0
	v_pk_mul_f32 v[50:51], v[50:51], v[56:57]
	v_add_f32_e32 v29, 1.0, v29
	v_rcp_f32_e32 v56, v29
	v_mul_f32_e32 v29, 0xbfb8aa3b, v55
	v_exp_f32_e32 v29, v29
	v_cvt_pk_bf16_f32 v50, v50, v51
	v_add_f32_e32 v29, 1.0, v29
	v_rcp_f32_e32 v57, v29
	s_nop 0
	v_pk_mul_f32 v[54:55], v[56:57], v[54:55]
	s_nop 0
	v_pk_mul_f32 v[52:53], v[52:53], v[54:55]
	s_nop 0
	v_cvt_pk_bf16_f32 v51, v52, v53
	v_mov_b64_e32 v[238:239], v[50:51]
	global_store_dwordx4 v[64:65], v[236:239], off offset:2112
	v_mov_b64_e32 v[50:51], v[208:209]
	v_lshlrev_b32_e32 v52, 16, v50
	v_mul_f32_e32 v29, 0xbfb8aa3b, v52
	v_exp_f32_e32 v29, v29
	v_and_b32_e32 v53, 0xffff0000, v50
	v_lshlrev_b32_e32 v50, 16, v51
	v_and_b32_e32 v51, 0xffff0000, v51
	v_add_f32_e32 v29, 1.0, v29
	v_rcp_f32_e32 v54, v29
	v_mul_f32_e32 v29, 0xbfb8aa3b, v53
	v_exp_f32_e32 v29, v29
	s_nop 0
	v_add_f32_e32 v29, 1.0, v29
	v_rcp_f32_e32 v55, v29
	v_mul_f32_e32 v29, 0xbfb8aa3b, v50
	v_exp_f32_e32 v29, v29
	v_pk_mul_f32 v[52:53], v[54:55], v[52:53]
	s_nop 0
	v_pk_mul_f32 v[46:47], v[46:47], v[52:53]
	v_add_f32_e32 v29, 1.0, v29
	v_rcp_f32_e32 v52, v29
	v_mul_f32_e32 v29, 0xbfb8aa3b, v51
	v_exp_f32_e32 v29, v29
	v_cvt_pk_bf16_f32 v46, v46, v47
	v_add_f32_e32 v29, 1.0, v29
	v_rcp_f32_e32 v53, v29
	s_nop 0
	v_pk_mul_f32 v[50:51], v[52:53], v[50:51]
	s_nop 0
	v_pk_mul_f32 v[48:49], v[48:49], v[50:51]
	s_nop 0
	v_cvt_pk_bf16_f32 v47, v48, v49
	v_mov_b64_e32 v[240:241], v[46:47]
	v_mov_b64_e32 v[46:47], v[210:211]
	v_lshlrev_b32_e32 v48, 16, v46
	v_mul_f32_e32 v29, 0xbfb8aa3b, v48
	v_exp_f32_e32 v29, v29
	v_and_b32_e32 v49, 0xffff0000, v46
; __device__ __forceinline__ unsigned pk2(float lo, float hi) { f32x2_t v = {lo, hi}; bf16x2_t b = __builtin_convertvector(v, bf16x2_t); return __builtin_bit_cast(unsigned, b); }
; __device__ __forceinline__ float bflo(unsigned u) { return __uint_as_float(u << 16); }
; __device__ __forceinline__ float bfhi(unsigned u) { return __uint_as_float(u & 0xffff0000u); }
; __device__ __forceinline__ float frcp(float x) { return __builtin_amdgcn_rcpf(x); }
; __device__ __forceinline__ float silu(float x) { return x * frcp(1.f + fexp(-x)); }
; __device__ __forceinline__ void mem_unit(const Args& a, int l, LAS unsigned char* lds, int b, int hm, int qb) {
;     ...
; #pragma unroll
;     for (int qt = 0; qt < 2; ++qt) {
;         const float inv = frcp(ol[qt][0]);
;         const size_t row = rowbase + q0 + qt * 16 + fr;
; #pragma unroll
;         for (int dt = 0; dt < 8; ++dt) { const int d0 = dt * 16 + fq * 4;
;             const u32x2 z = *(const u32x2*)(proj + row * NCOL + CZ + 1024 + hm * 128 + d0);
;             u32x2 y; y.x = pk2(o[dt][qt][0] * inv * silu(bflo(z.x)), o[dt][qt][1] * inv * silu(bfhi(z.x))); y.y = pk2(o[dt][qt][2] * inv * silu(bflo(z.y)), o[dt][qt][3] * inv * silu(bfhi(z.y)));
;             *(u32x2*)(proj + row * NCOL + CQM + hm * 128 + d0) = y; }
	v_lshlrev_b32_e32 v46, 16, v47
	v_and_b32_e32 v47, 0xffff0000, v47
	v_add_f32_e32 v29, 1.0, v29
	v_rcp_f32_e32 v50, v29
	v_mul_f32_e32 v29, 0xbfb8aa3b, v49
	v_exp_f32_e32 v29, v29
	s_nop 0
	v_add_f32_e32 v29, 1.0, v29
	v_rcp_f32_e32 v51, v29
	v_mul_f32_e32 v29, 0xbfb8aa3b, v46
	v_exp_f32_e32 v29, v29
	v_pk_mul_f32 v[48:49], v[50:51], v[48:49]
	s_nop 0
	v_pk_mul_f32 v[42:43], v[42:43], v[48:49]
	v_add_f32_e32 v29, 1.0, v29
	v_rcp_f32_e32 v48, v29
	v_mul_f32_e32 v29, 0xbfb8aa3b, v47
	v_exp_f32_e32 v29, v29
	v_cvt_pk_bf16_f32 v42, v42, v43
	v_add_f32_e32 v29, 1.0, v29
	v_rcp_f32_e32 v49, v29
	s_nop 0
	v_pk_mul_f32 v[46:47], v[48:49], v[46:47]
	s_nop 0
	v_pk_mul_f32 v[44:45], v[44:45], v[46:47]
	s_nop 0
	v_cvt_pk_bf16_f32 v43, v44, v45
	v_mov_b64_e32 v[242:243], v[42:43]
	global_store_dwordx4 v[64:65], v[240:243], off offset:2176
	v_mov_b64_e32 v[42:43], v[212:213]
	v_lshlrev_b32_e32 v44, 16, v42
	v_mul_f32_e32 v29, 0xbfb8aa3b, v44
	v_exp_f32_e32 v29, v29
	v_and_b32_e32 v45, 0xffff0000, v42
	v_lshlrev_b32_e32 v42, 16, v43
	v_and_b32_e32 v43, 0xffff0000, v43
	v_add_f32_e32 v29, 1.0, v29
	v_rcp_f32_e32 v46, v29
	v_mul_f32_e32 v29, 0xbfb8aa3b, v45
	v_exp_f32_e32 v29, v29
	s_nop 0
	v_add_f32_e32 v29, 1.0, v29
	v_rcp_f32_e32 v47, v29
	v_mul_f32_e32 v29, 0xbfb8aa3b, v42
	v_exp_f32_e32 v29, v29
	v_pk_mul_f32 v[44:45], v[46:47], v[44:45]
	s_nop 0
	v_pk_mul_f32 v[38:39], v[38:39], v[44:45]
	v_add_f32_e32 v29, 1.0, v29
	v_rcp_f32_e32 v44, v29
	v_mul_f32_e32 v29, 0xbfb8aa3b, v43
	v_exp_f32_e32 v29, v29
	v_cvt_pk_bf16_f32 v38, v38, v39
	v_add_f32_e32 v29, 1.0, v29
	v_rcp_f32_e32 v45, v29
	s_nop 0
	v_pk_mul_f32 v[42:43], v[44:45], v[42:43]
	s_nop 0
	v_pk_mul_f32 v[40:41], v[40:41], v[42:43]
	s_nop 0
	v_cvt_pk_bf16_f32 v39, v40, v41
	v_mov_b64_e32 v[180:181], v[38:39]
	v_mov_b64_e32 v[38:39], v[214:215]
	v_lshlrev_b32_e32 v40, 16, v38
	v_mul_f32_e32 v29, 0xbfb8aa3b, v40
	v_exp_f32_e32 v29, v29
	v_and_b32_e32 v41, 0xffff0000, v38
	v_lshlrev_b32_e32 v38, 16, v39
	v_and_b32_e32 v39, 0xffff0000, v39
	v_add_f32_e32 v29, 1.0, v29
	v_rcp_f32_e32 v42, v29
	v_mul_f32_e32 v29, 0xbfb8aa3b, v41
	v_exp_f32_e32 v29, v29
	s_nop 0
	v_add_f32_e32 v29, 1.0, v29
	v_rcp_f32_e32 v43, v29
	v_mul_f32_e32 v29, 0xbfb8aa3b, v38
	v_exp_f32_e32 v29, v29
	v_pk_mul_f32 v[40:41], v[42:43], v[40:41]
	s_nop 0
	v_pk_mul_f32 v[34:35], v[34:35], v[40:41]
	v_add_f32_e32 v29, 1.0, v29
	v_rcp_f32_e32 v40, v29
	v_mul_f32_e32 v29, 0xbfb8aa3b, v39
	v_exp_f32_e32 v29, v29
	v_cvt_pk_bf16_f32 v34, v34, v35
	v_add_f32_e32 v29, 1.0, v29
	v_rcp_f32_e32 v41, v29
	s_nop 0
	v_pk_mul_f32 v[38:39], v[40:41], v[38:39]
	s_nop 0
	v_pk_mul_f32 v[36:37], v[36:37], v[38:39]
	s_nop 0
	v_cvt_pk_bf16_f32 v35, v36, v37
	v_mov_b64_e32 v[182:183], v[34:35]
	global_store_dwordx4 v[64:65], v[180:183], off offset:2240
	v_rcp_f32_e32 v34, v28
	v_lshl_add_u64 v[28:29], v[158:159], 0, s[6:7]
	v_lshl_add_u64 v[28:29], v[28:29], 0, v[144:145]
	v_lshl_add_u64 v[36:37], v[28:29], 0, s[4:5]
	v_add_co_u32_e32 v28, vcc, s26, v28
	v_pk_mul_f32 v[30:31], v[34:35], v[30:31] op_sel_hi:[0,1]
	s_nop 0
	v_addc_co_u32_e32 v29, vcc, 0, v29, vcc
	v_mov_b64_e32 v[28:29], v[216:217]
	v_pk_mul_f32 v[32:33], v[34:35], v[32:33] op_sel_hi:[0,1]
	v_pk_mul_f32 v[24:25], v[34:35], v[24:25] op_sel_hi:[0,1]
	v_pk_mul_f32 v[26:27], v[34:35], v[26:27] op_sel_hi:[0,1]
	v_pk_mul_f32 v[20:21], v[34:35], v[20:21] op_sel_hi:[0,1]
	v_pk_mul_f32 v[22:23], v[34:35], v[22:23] op_sel_hi:[0,1]
	v_pk_mul_f32 v[16:17], v[34:35], v[16:17] op_sel_hi:[0,1]
	v_pk_mul_f32 v[18:19], v[34:35], v[18:19] op_sel_hi:[0,1]
	v_pk_mul_f32 v[12:13], v[34:35], v[12:13] op_sel_hi:[0,1]
	v_pk_mul_f32 v[14:15], v[34:35], v[14:15] op_sel_hi:[0,1]
	v_pk_mul_f32 v[8:9], v[34:35], v[8:9] op_sel_hi:[0,1]
	v_pk_mul_f32 v[10:11], v[34:35], v[10:11] op_sel_hi:[0,1]
	v_pk_mul_f32 v[4:5], v[34:35], v[4:5] op_sel_hi:[0,1]
	v_pk_mul_f32 v[6:7], v[34:35], v[6:7] op_sel_hi:[0,1]
	v_pk_mul_f32 v[0:1], v[34:35], v[0:1] op_sel_hi:[0,1]
	v_pk_mul_f32 v[2:3], v[34:35], v[2:3] op_sel_hi:[0,1]
	v_lshlrev_b32_e32 v38, 16, v28
	v_and_b32_e32 v39, 0xffff0000, v28
	v_mul_f32_e32 v28, 0xbfb8aa3b, v38
	v_exp_f32_e32 v28, v28
	s_nop 0
	v_add_f32_e32 v28, 1.0, v28
	v_rcp_f32_e32 v40, v28
	v_mul_f32_e32 v28, 0xbfb8aa3b, v39
	v_exp_f32_e32 v28, v28
	s_nop 0
	v_add_f32_e32 v28, 1.0, v28
	v_rcp_f32_e32 v41, v28
	v_lshlrev_b32_e32 v28, 16, v29
	v_and_b32_e32 v29, 0xffff0000, v29
	v_pk_mul_f32 v[38:39], v[40:41], v[38:39]
	s_nop 0
	v_pk_mul_f32 v[30:31], v[30:31], v[38:39]
	s_nop 0
	v_cvt_pk_bf16_f32 v30, v30, v31
	v_mul_f32_e32 v31, 0xbfb8aa3b, v28
	v_exp_f32_e32 v31, v31
	s_nop 0
	v_add_f32_e32 v31, 1.0, v31
	v_rcp_f32_e32 v38, v31
	v_mul_f32_e32 v31, 0xbfb8aa3b, v29
	v_exp_f32_e32 v31, v31
	s_nop 0
	v_add_f32_e32 v31, 1.0, v31
	v_rcp_f32_e32 v39, v31
	s_nop 0
	v_pk_mul_f32 v[28:29], v[38:39], v[28:29]
	s_nop 0
	v_pk_mul_f32 v[28:29], v[32:33], v[28:29]
	s_nop 0
	v_cvt_pk_bf16_f32 v31, v28, v29
	v_lshl_add_u64 v[28:29], v[156:157], 0, v[142:143]
	v_mov_b64_e32 v[232:233], v[30:31]
	v_mov_b64_e32 v[30:31], v[218:219]
	v_lshlrev_b32_e32 v32, 16, v30
	v_and_b32_e32 v33, 0xffff0000, v30
	v_mul_f32_e32 v30, 0xbfb8aa3b, v32
	v_exp_f32_e32 v30, v30
	s_nop 0
	v_add_f32_e32 v30, 1.0, v30
	v_rcp_f32_e32 v38, v30
	v_mul_f32_e32 v30, 0xbfb8aa3b, v33
	v_exp_f32_e32 v30, v30
	s_nop 0
	v_add_f32_e32 v30, 1.0, v30
	v_rcp_f32_e32 v39, v30
	v_lshlrev_b32_e32 v30, 16, v31
	v_and_b32_e32 v31, 0xffff0000, v31
	v_pk_mul_f32 v[32:33], v[38:39], v[32:33]
	s_nop 0
	v_pk_mul_f32 v[24:25], v[24:25], v[32:33]
	s_nop 0
	v_cvt_pk_bf16_f32 v24, v24, v25
	v_mul_f32_e32 v25, 0xbfb8aa3b, v30
	v_exp_f32_e32 v25, v25
	s_nop 0
	v_add_f32_e32 v25, 1.0, v25
; __device__ __forceinline__ unsigned pk2(float lo, float hi) { f32x2_t v = {lo, hi}; bf16x2_t b = __builtin_convertvector(v, bf16x2_t); return __builtin_bit_cast(unsigned, b); }
; __device__ __forceinline__ float bflo(unsigned u) { return __uint_as_float(u << 16); }
; __device__ __forceinline__ float bfhi(unsigned u) { return __uint_as_float(u & 0xffff0000u); }
; __device__ __forceinline__ float frcp(float x) { return __builtin_amdgcn_rcpf(x); }
; __device__ __forceinline__ float silu(float x) { return x * frcp(1.f + fexp(-x)); }
; __device__ __forceinline__ void mem_unit(const Args& a, int l, LAS unsigned char* lds, int b, int hm, int qb) {
;     ...
; #pragma unroll
;     for (int qt = 0; qt < 2; ++qt) {
;         const float inv = frcp(ol[qt][0]);
;         const size_t row = rowbase + q0 + qt * 16 + fr;
; #pragma unroll
;         for (int dt = 0; dt < 8; ++dt) { const int d0 = dt * 16 + fq * 4;
;             const u32x2 z = *(const u32x2*)(proj + row * NCOL + CZ + 1024 + hm * 128 + d0);
;             u32x2 y; y.x = pk2(o[dt][qt][0] * inv * silu(bflo(z.x)), o[dt][qt][1] * inv * silu(bfhi(z.x))); y.y = pk2(o[dt][qt][2] * inv * silu(bflo(z.y)), o[dt][qt][3] * inv * silu(bfhi(z.y)));
;             *(u32x2*)(proj + row * NCOL + CQM + hm * 128 + d0) = y; }
; __global__ void __launch_bounds__(512) hymba_fwd(Args a) {
;     ...
;             for (int u0 = bx; u0 < 256; u0 += G) { const int u = (G == 256) ? (u0 & 7) * 32 + (u0 >> 3) : u0;
;                 mem_unit(a, l, lds, u >> 5, (u >> 3) & 3, u & 7); }
	v_rcp_f32_e32 v32, v25
	v_mul_f32_e32 v25, 0xbfb8aa3b, v31
	v_exp_f32_e32 v25, v25
	s_nop 0
	v_add_f32_e32 v25, 1.0, v25
	v_rcp_f32_e32 v33, v25
	s_nop 0
	v_pk_mul_f32 v[30:31], v[32:33], v[30:31]
	s_nop 0
	v_pk_mul_f32 v[26:27], v[26:27], v[30:31]
	s_nop 0
	v_cvt_pk_bf16_f32 v25, v26, v27
	v_mov_b64_e32 v[234:235], v[24:25]
	global_store_dwordx4 v[28:29], v[232:235], off offset:2048
	v_mov_b64_e32 v[24:25], v[220:221]
	v_lshlrev_b32_e32 v26, 16, v24
	v_and_b32_e32 v27, 0xffff0000, v24
	v_mul_f32_e32 v24, 0xbfb8aa3b, v26
	v_exp_f32_e32 v24, v24
	s_nop 0
	v_add_f32_e32 v24, 1.0, v24
	v_rcp_f32_e32 v30, v24
	v_mul_f32_e32 v24, 0xbfb8aa3b, v27
	v_exp_f32_e32 v24, v24
	s_nop 0
	v_add_f32_e32 v24, 1.0, v24
	v_rcp_f32_e32 v31, v24
	v_lshlrev_b32_e32 v24, 16, v25
	v_and_b32_e32 v25, 0xffff0000, v25
	v_pk_mul_f32 v[26:27], v[30:31], v[26:27]
	s_nop 0
	v_pk_mul_f32 v[20:21], v[20:21], v[26:27]
	s_nop 0
	v_cvt_pk_bf16_f32 v20, v20, v21
	v_mul_f32_e32 v21, 0xbfb8aa3b, v24
	v_exp_f32_e32 v21, v21
	s_nop 0
	v_add_f32_e32 v21, 1.0, v21
	v_rcp_f32_e32 v26, v21
	v_mul_f32_e32 v21, 0xbfb8aa3b, v25
	v_exp_f32_e32 v21, v21
	s_nop 0
	v_add_f32_e32 v21, 1.0, v21
	v_rcp_f32_e32 v27, v21
	s_nop 0
	v_pk_mul_f32 v[24:25], v[26:27], v[24:25]
	s_nop 0
	v_pk_mul_f32 v[22:23], v[22:23], v[24:25]
	s_nop 0
	v_cvt_pk_bf16_f32 v21, v22, v23
	v_mov_b64_e32 v[236:237], v[20:21]
	v_mov_b64_e32 v[20:21], v[222:223]
	v_lshlrev_b32_e32 v22, 16, v20
	v_and_b32_e32 v23, 0xffff0000, v20
	v_mul_f32_e32 v20, 0xbfb8aa3b, v22
	v_exp_f32_e32 v20, v20
	s_nop 0
	v_add_f32_e32 v20, 1.0, v20
	v_rcp_f32_e32 v24, v20
	v_mul_f32_e32 v20, 0xbfb8aa3b, v23
	v_exp_f32_e32 v20, v20
	s_nop 0
	v_add_f32_e32 v20, 1.0, v20
	v_rcp_f32_e32 v25, v20
	v_lshlrev_b32_e32 v20, 16, v21
	v_and_b32_e32 v21, 0xffff0000, v21
	v_pk_mul_f32 v[22:23], v[24:25], v[22:23]
	s_nop 0
	v_pk_mul_f32 v[16:17], v[16:17], v[22:23]
	s_nop 0
	v_cvt_pk_bf16_f32 v16, v16, v17
	v_mul_f32_e32 v17, 0xbfb8aa3b, v20
	v_exp_f32_e32 v17, v17
	s_nop 0
	v_add_f32_e32 v17, 1.0, v17
	v_rcp_f32_e32 v22, v17
	v_mul_f32_e32 v17, 0xbfb8aa3b, v21
	v_exp_f32_e32 v17, v17
	s_nop 0
	v_add_f32_e32 v17, 1.0, v17
	v_rcp_f32_e32 v23, v17
	s_nop 0
	v_pk_mul_f32 v[20:21], v[22:23], v[20:21]
	s_nop 0
	v_pk_mul_f32 v[18:19], v[18:19], v[20:21]
	s_nop 0
	v_cvt_pk_bf16_f32 v17, v18, v19
	v_mov_b64_e32 v[238:239], v[16:17]
	global_store_dwordx4 v[28:29], v[236:239], off offset:2112
	v_mov_b64_e32 v[16:17], v[224:225]
	v_lshlrev_b32_e32 v18, 16, v16
	v_and_b32_e32 v19, 0xffff0000, v16
	v_mul_f32_e32 v16, 0xbfb8aa3b, v18
	v_exp_f32_e32 v16, v16
	s_nop 0
	v_add_f32_e32 v16, 1.0, v16
	v_rcp_f32_e32 v20, v16
	v_mul_f32_e32 v16, 0xbfb8aa3b, v19
	v_exp_f32_e32 v16, v16
	s_nop 0
	v_add_f32_e32 v16, 1.0, v16
	v_rcp_f32_e32 v21, v16
	v_lshlrev_b32_e32 v16, 16, v17
	v_and_b32_e32 v17, 0xffff0000, v17
	v_pk_mul_f32 v[18:19], v[20:21], v[18:19]
	s_nop 0
	v_pk_mul_f32 v[12:13], v[12:13], v[18:19]
	s_nop 0
	v_cvt_pk_bf16_f32 v12, v12, v13
	v_mul_f32_e32 v13, 0xbfb8aa3b, v16
	v_exp_f32_e32 v13, v13
	s_nop 0
	v_add_f32_e32 v13, 1.0, v13
	v_rcp_f32_e32 v18, v13
	v_mul_f32_e32 v13, 0xbfb8aa3b, v17
	v_exp_f32_e32 v13, v13
	s_nop 0
	v_add_f32_e32 v13, 1.0, v13
	v_rcp_f32_e32 v19, v13
	s_nop 0
	v_pk_mul_f32 v[16:17], v[18:19], v[16:17]
	s_nop 0
	v_pk_mul_f32 v[14:15], v[14:15], v[16:17]
	s_nop 0
	v_cvt_pk_bf16_f32 v13, v14, v15
	v_mov_b64_e32 v[240:241], v[12:13]
	v_mov_b64_e32 v[12:13], v[226:227]
	v_lshlrev_b32_e32 v14, 16, v12
	v_and_b32_e32 v15, 0xffff0000, v12
	v_mul_f32_e32 v12, 0xbfb8aa3b, v14
	v_exp_f32_e32 v12, v12
	s_nop 0
	v_add_f32_e32 v12, 1.0, v12
	v_rcp_f32_e32 v16, v12
	v_mul_f32_e32 v12, 0xbfb8aa3b, v15
	v_exp_f32_e32 v12, v12
	s_nop 0
	v_add_f32_e32 v12, 1.0, v12
	v_rcp_f32_e32 v17, v12
	v_lshlrev_b32_e32 v12, 16, v13
	v_and_b32_e32 v13, 0xffff0000, v13
	v_pk_mul_f32 v[14:15], v[16:17], v[14:15]
	s_nop 0
	v_pk_mul_f32 v[8:9], v[8:9], v[14:15]
	s_nop 0
	v_cvt_pk_bf16_f32 v8, v8, v9
	v_mul_f32_e32 v9, 0xbfb8aa3b, v12
	v_exp_f32_e32 v9, v9
	s_nop 0
	v_add_f32_e32 v9, 1.0, v9
	v_rcp_f32_e32 v14, v9
	v_mul_f32_e32 v9, 0xbfb8aa3b, v13
	v_exp_f32_e32 v9, v9
	s_nop 0
	v_add_f32_e32 v9, 1.0, v9
	v_rcp_f32_e32 v15, v9
	s_nop 0
	v_pk_mul_f32 v[12:13], v[14:15], v[12:13]
	s_nop 0
	v_pk_mul_f32 v[10:11], v[10:11], v[12:13]
	s_nop 0
	v_cvt_pk_bf16_f32 v9, v10, v11
	v_mov_b64_e32 v[242:243], v[8:9]
	global_store_dwordx4 v[28:29], v[240:243], off offset:2176
	v_mov_b64_e32 v[8:9], v[228:229]
	v_lshlrev_b32_e32 v10, 16, v8
	v_and_b32_e32 v11, 0xffff0000, v8
	v_mul_f32_e32 v8, 0xbfb8aa3b, v10
	v_exp_f32_e32 v8, v8
	s_nop 0
	v_add_f32_e32 v8, 1.0, v8
	v_rcp_f32_e32 v12, v8
	v_mul_f32_e32 v8, 0xbfb8aa3b, v11
	v_exp_f32_e32 v8, v8
	s_nop 0
	v_add_f32_e32 v8, 1.0, v8
	v_rcp_f32_e32 v13, v8
	v_lshlrev_b32_e32 v8, 16, v9
	v_and_b32_e32 v9, 0xffff0000, v9
	v_pk_mul_f32 v[10:11], v[12:13], v[10:11]
	s_nop 0
	v_pk_mul_f32 v[4:5], v[4:5], v[10:11]
	s_nop 0
	v_cvt_pk_bf16_f32 v4, v4, v5
	v_mul_f32_e32 v5, 0xbfb8aa3b, v8
	v_exp_f32_e32 v5, v5
	s_nop 0
	v_add_f32_e32 v5, 1.0, v5
	v_rcp_f32_e32 v10, v5
	v_mul_f32_e32 v5, 0xbfb8aa3b, v9
	v_exp_f32_e32 v5, v5
	s_nop 0
	v_add_f32_e32 v5, 1.0, v5
	v_rcp_f32_e32 v11, v5
	s_nop 0
	v_pk_mul_f32 v[8:9], v[10:11], v[8:9]
	s_nop 0
	v_pk_mul_f32 v[6:7], v[6:7], v[8:9]
	s_nop 0
	v_cvt_pk_bf16_f32 v5, v6, v7
	v_mov_b64_e32 v[180:181], v[4:5]
	v_mov_b64_e32 v[4:5], v[230:231]
	v_lshlrev_b32_e32 v6, 16, v4
	v_and_b32_e32 v7, 0xffff0000, v4
	v_mul_f32_e32 v4, 0xbfb8aa3b, v6
	v_exp_f32_e32 v4, v4
	s_nop 0
	v_add_f32_e32 v4, 1.0, v4
	v_rcp_f32_e32 v8, v4
	v_mul_f32_e32 v4, 0xbfb8aa3b, v7
	v_exp_f32_e32 v4, v4
	s_nop 0
	v_add_f32_e32 v4, 1.0, v4
	v_rcp_f32_e32 v9, v4
	v_lshlrev_b32_e32 v4, 16, v5
	v_and_b32_e32 v5, 0xffff0000, v5
	v_pk_mul_f32 v[6:7], v[8:9], v[6:7]
	s_nop 0
	v_pk_mul_f32 v[0:1], v[0:1], v[6:7]
	s_nop 0
	v_cvt_pk_bf16_f32 v0, v0, v1
	v_mul_f32_e32 v1, 0xbfb8aa3b, v4
	v_exp_f32_e32 v1, v1
	s_nop 0
	v_add_f32_e32 v1, 1.0, v1
	v_rcp_f32_e32 v6, v1
	v_mul_f32_e32 v1, 0xbfb8aa3b, v5
	v_exp_f32_e32 v1, v1
	s_nop 0
	v_add_f32_e32 v1, 1.0, v1
	v_rcp_f32_e32 v7, v1
	s_nop 0
	v_pk_mul_f32 v[4:5], v[6:7], v[4:5]
	s_nop 0
	v_pk_mul_f32 v[2:3], v[2:3], v[4:5]
	s_nop 0
	v_cvt_pk_bf16_f32 v1, v2, v3
	v_mov_b64_e32 v[182:183], v[0:1]
	global_store_dwordx4 v[28:29], v[180:183], off offset:2240
	s_cbranch_scc0 .LBB0_519
